# scan: ds_read->MFMA chains merged across groups into regions (address setups duplicated into free VGPRs, fragments rotated over a 6-buffer pool, 5 reads ahead) plus remaining single-temp runs pipeline
# baseline (speedup 1.0000x reference)
; __device__ __forceinline__ unsigned cvt_pk(float lo, float hi) { unsigned r; asm volatile("v_cvt_pk_bf16_f32 %0, %1, %2" : "=v"(r) : "v"(lo), "v"(hi)); return r; }
; template <int SPLIT> __device__ __forceinline__ void scan_item(const Params& p, unsigned char* smem, const int item, const int vh) {
;     ...
;             __syncthreads();
;             const float m_old = sc[0], M127 = sc[1];
;             const float decay = __expf(m_old - M127);
;             {
;                 const f32x4 a4 = *(const f32x4*)(a_s + sp * 4);
;                 float wsv[4];
; #pragma unroll
;                 for (int i = 0; i < 4; ++i) wsv[i] = __expf(a4[i] - M127);
; #pragma unroll
;                 for (int i = 0; i < 4; ++i) { const u32x4 k = kreg[i]; u32x4 w;
;                     w.x = cvt_pk(bflo(k.x) * wsv[i], bfhi(k.x) * wsv[i]); w.y = cvt_pk(bflo(k.y) * wsv[i], bfhi(k.y) * wsv[i]);
;                     w.z = cvt_pk(bflo(k.z) * wsv[i], bfhi(k.z) * wsv[i]); w.w = cvt_pk(bflo(k.w) * wsv[i], bfhi(k.w) * wsv[i]);
;                     *(u32x4*)(KP + swz(sp * 4 + i, ch)) = w; }
; #pragma unroll
;                 for (int e2 = 0; e2 < 4; ++e2) {
;                     const unsigned k0 = kreg[0][e2], k1 = kreg[1][e2], k2 = kreg[2][e2], k3 = kreg[3][e2];
;                     const unsigned v0 = vreg[0][e2], v1 = vreg[1][e2], v2 = vreg[2][e2], v3 = vreg[3][e2];
;                     const int d0 = ch * 8 + 2 * e2, d1 = d0 + 1; const int co = (sp & 1) * 8;
;                     u32x2 o;
;                     o.x = cvt_pk(bflo(k0) * wsv[0], bflo(k1) * wsv[1]); o.y = cvt_pk(bflo(k2) * wsv[2], bflo(k3) * wsv[3]);
;                     *(u32x2*)(KT + swz(d0, sp >> 1) + co) = o;
;                     o.x = cvt_pk(bfhi(k0) * wsv[0], bfhi(k1) * wsv[1]); o.y = cvt_pk(bfhi(k2) * wsv[2], bfhi(k3) * wsv[3]);
;                     *(u32x2*)(KT + swz(d1, sp >> 1) + co) = o;
;                     o.x = (v0 & 0xffffu) | (v1 << 16); o.y = (v2 & 0xffffu) | (v3 << 16);
;                     *(u32x2*)(VT + swz(d0, sp >> 1) + co) = o;
;                     o.x = (v0 >> 16) | (v1 & 0xffff0000u); o.y = (v2 >> 16) | (v3 & 0xffff0000u);
;                     *(u32x2*)(VT + swz(d1, sp >> 1) + co) = o;
;                 }
;             }
;             const size_t rowl = (size_t)(rfirst + rstep * (j * 128 + wid * 16 + li));
;             __syncthreads();
;             SCAN_LOAD(jn);
.LBB0_294:
	s_or_b64 exec, exec, s[86:87]
	v_mov_b32_e32 v80, s94
	s_waitcnt lgkmcnt(0)
	s_barrier
	ds_read_b64 v[80:81], v80
	ds_read_b128 v[82:85], v116
	s_waitcnt vmcnt(11)
	v_lshlrev_b32_e32 v86, 16, v44
	v_and_b32_e32 v44, 0xffff0000, v44
	v_lshlrev_b32_e32 v88, 16, v45
	v_and_b32_e32 v45, 0xffff0000, v45
	s_waitcnt lgkmcnt(0)
	v_sub_f32_e32 v82, v82, v81
	v_mul_f32_e32 v82, 0x3fb8aa3b, v82
	v_exp_f32_e32 v82, v82
	v_sub_f32_e32 v83, v83, v81
	v_mul_f32_e32 v83, 0x3fb8aa3b, v83
	v_exp_f32_e32 v83, v83
	v_sub_f32_e32 v84, v84, v81
	v_mul_f32_e32 v84, 0x3fb8aa3b, v84
	v_lshlrev_b32_e32 v90, 16, v46
	v_and_b32_e32 v46, 0xffff0000, v46
	v_exp_f32_e32 v84, v84
	v_sub_f32_e32 v85, v85, v81
	v_mul_f32_e32 v86, v82, v86
	v_mul_f32_e32 v87, v82, v44
	v_cvt_pk_bf16_f32 v44, v86, v87
	v_mul_f32_e32 v88, v82, v88
	v_mul_f32_e32 v89, v82, v45
	v_cvt_pk_bf16_f32 v45, v88, v89
	v_mul_f32_e32 v90, v82, v90
	v_mul_f32_e32 v91, v82, v46
	v_cvt_pk_bf16_f32 v46, v90, v91
	v_lshlrev_b32_e32 v95, 16, v47
	v_and_b32_e32 v47, 0xffff0000, v47
	v_mul_f32_e32 v85, 0x3fb8aa3b, v85
	v_mul_f32_e32 v95, v82, v95
	v_mul_f32_e32 v82, v82, v47
	v_cvt_pk_bf16_f32 v47, v95, v82
	ds_write_b128 v154, v[44:47]
	s_waitcnt vmcnt(10)
	v_lshlrev_b32_e32 v44, 16, v40
	v_and_b32_e32 v40, 0xffff0000, v40
	v_lshlrev_b32_e32 v46, 16, v41
	v_and_b32_e32 v41, 0xffff0000, v41
	v_lshlrev_b32_e32 v112, 16, v42
	v_and_b32_e32 v42, 0xffff0000, v42
	v_exp_f32_e32 v85, v85
	v_mul_f32_e32 v44, v83, v44
	v_mul_f32_e32 v45, v83, v40
	v_cvt_pk_bf16_f32 v40, v44, v45
	v_mul_f32_e32 v46, v83, v46
	v_mul_f32_e32 v47, v83, v41
	v_cvt_pk_bf16_f32 v41, v46, v47
	v_mul_f32_e32 v112, v83, v112
	v_mul_f32_e32 v164, v83, v42
	v_cvt_pk_bf16_f32 v42, v112, v164
	v_lshlrev_b32_e32 v165, 16, v43
	v_and_b32_e32 v43, 0xffff0000, v43
	v_mul_f32_e32 v165, v83, v165
	v_mul_f32_e32 v83, v83, v43
	v_cvt_pk_bf16_f32 v43, v165, v83
	ds_write_b128 v155, v[40:43]
	s_waitcnt vmcnt(9)
	v_lshlrev_b32_e32 v40, 16, v36
	v_and_b32_e32 v36, 0xffff0000, v36
	v_lshlrev_b32_e32 v42, 16, v37
	v_and_b32_e32 v37, 0xffff0000, v37
	v_lshlrev_b32_e32 v166, 16, v38
	v_and_b32_e32 v38, 0xffff0000, v38
	v_mul_f32_e32 v40, v84, v40
	v_mul_f32_e32 v41, v84, v36
	v_cvt_pk_bf16_f32 v36, v40, v41
	v_mul_f32_e32 v42, v84, v42
	v_mul_f32_e32 v43, v84, v37
	v_cvt_pk_bf16_f32 v37, v42, v43
	v_mul_f32_e32 v166, v84, v166
	v_mul_f32_e32 v167, v84, v38
	v_cvt_pk_bf16_f32 v38, v166, v167
	v_lshlrev_b32_e32 v168, 16, v39
	v_and_b32_e32 v39, 0xffff0000, v39
	v_mul_f32_e32 v168, v84, v168
	v_mul_f32_e32 v84, v84, v39
	v_cvt_pk_bf16_f32 v39, v168, v84
	ds_write_b128 v156, v[36:39]
	s_waitcnt vmcnt(7)
	v_lshlrev_b32_e32 v36, 16, v32
	v_and_b32_e32 v32, 0xffff0000, v32
	v_lshlrev_b32_e32 v38, 16, v33
	v_and_b32_e32 v33, 0xffff0000, v33
	v_lshlrev_b32_e32 v169, 16, v34
	v_and_b32_e32 v34, 0xffff0000, v34
	v_mul_f32_e32 v36, v85, v36
	v_mul_f32_e32 v37, v85, v32
	v_cvt_pk_bf16_f32 v32, v36, v37
	v_mul_f32_e32 v38, v85, v38
	v_mul_f32_e32 v39, v85, v33
	v_cvt_pk_bf16_f32 v33, v38, v39
	v_mul_f32_e32 v169, v85, v169
	v_mul_f32_e32 v171, v85, v34
	v_cvt_pk_bf16_f32 v34, v169, v171
	v_lshlrev_b32_e32 v172, 16, v35
	v_and_b32_e32 v35, 0xffff0000, v35
	v_mul_f32_e32 v172, v85, v172
	v_mul_f32_e32 v85, v85, v35
	v_cvt_pk_bf16_f32 v35, v172, v85
	ds_write_b128 v157, v[32:35]
	v_cvt_pk_bf16_f32 v32, v86, v44
	v_cvt_pk_bf16_f32 v33, v40, v36
	v_add_u32_e32 v34, v120, v136
	ds_write_b64 v34, v[32:33]
	v_cvt_pk_bf16_f32 v32, v87, v45
	v_cvt_pk_bf16_f32 v33, v41, v37
	v_add_u32_e32 v34, v120, v137
	ds_write_b64 v34, v[32:33]
	s_waitcnt vmcnt(4)
	v_lshlrev_b32_e32 v32, 16, v4
	v_lshlrev_b32_e32 v33, 16, v16
	v_and_or_b32 v32, v0, s91, v32
	v_and_or_b32 v33, v8, s91, v33
	v_add_u32_e32 v34, v121, v136
	v_lshrrev_b32_e32 v0, 16, v0
	ds_write_b64 v34, v[32:33] offset:32768
	v_and_or_b32 v32, v4, s90, v0
	v_lshrrev_b32_e32 v0, 16, v8
	v_and_or_b32 v33, v16, s90, v0
	v_add_u32_e32 v0, v121, v137
	ds_write_b64 v0, v[32:33] offset:32768
	v_add_u32_e32 v0, v120, v138
	v_cvt_pk_bf16_f32 v32, v88, v46
	v_cvt_pk_bf16_f32 v33, v42, v38
	ds_write_b64 v0, v[32:33]
	v_add_u32_e32 v0, v120, v139
	v_cvt_pk_bf16_f32 v32, v89, v47
	v_cvt_pk_bf16_f32 v33, v43, v39
	ds_write_b64 v0, v[32:33]
	v_lshlrev_b32_e32 v0, 16, v5
	v_and_or_b32 v32, v1, s91, v0
	v_lshlrev_b32_e32 v0, 16, v17
	v_and_or_b32 v33, v9, s91, v0
	v_add_u32_e32 v0, v121, v138
	ds_write_b64 v0, v[32:33] offset:32768
	v_lshrrev_b32_e32 v0, 16, v1
	v_lshrrev_b32_e32 v1, 16, v9
	v_and_or_b32 v0, v5, s90, v0
	v_and_or_b32 v1, v17, s90, v1
	v_add_u32_e32 v4, v121, v139
	ds_write_b64 v4, v[0:1] offset:32768
	v_cvt_pk_bf16_f32 v0, v90, v112
	v_cvt_pk_bf16_f32 v1, v166, v169
	v_add_u32_e32 v4, v120, v140
	ds_write_b64 v4, v[0:1]
	v_cvt_pk_bf16_f32 v0, v91, v164
	v_cvt_pk_bf16_f32 v1, v167, v171
	v_add_u32_e32 v4, v120, v141
	ds_write_b64 v4, v[0:1]
	v_lshlrev_b32_e32 v0, 16, v6
	v_lshlrev_b32_e32 v1, 16, v18
	v_and_or_b32 v0, v2, s91, v0
	v_and_or_b32 v1, v10, s91, v1
	v_add_u32_e32 v4, v121, v140
	ds_write_b64 v4, v[0:1] offset:32768
	v_lshrrev_b32_e32 v0, 16, v2
	v_lshrrev_b32_e32 v1, 16, v10
	v_and_or_b32 v0, v6, s90, v0
	v_and_or_b32 v1, v18, s90, v1
	v_add_u32_e32 v2, v121, v141
	ds_write_b64 v2, v[0:1] offset:32768
	v_cvt_pk_bf16_f32 v0, v95, v165
	v_cvt_pk_bf16_f32 v1, v168, v172
	v_add_u32_e32 v2, v120, v142
	ds_write_b64 v2, v[0:1]
	v_cvt_pk_bf16_f32 v0, v82, v83
	v_cvt_pk_bf16_f32 v1, v84, v85
	v_add_u32_e32 v2, v120, v143
	ds_write_b64 v2, v[0:1]
	v_lshlrev_b32_e32 v0, 16, v7
	v_lshlrev_b32_e32 v1, 16, v19
	v_and_or_b32 v0, v3, s91, v0
	v_and_or_b32 v1, v11, s91, v1
	v_add_u32_e32 v2, v121, v142
	ds_write_b64 v2, v[0:1] offset:32768
	v_lshrrev_b32_e32 v0, 16, v3
	v_lshrrev_b32_e32 v1, 16, v11
	v_and_or_b32 v0, v7, s90, v0
	v_and_or_b32 v1, v19, s90, v1
	v_add_u32_e32 v2, v121, v143
	s_lshl_b32 s0, vcc_lo, 7
	ds_write_b64 v2, v[0:1] offset:32768
	v_or_b32_e32 v0, s0, v113
	v_mul_lo_u32 v0, v0, s3
	v_add_u32_e32 v4, s33, v0
	v_ashrrev_i32_e32 v5, 31, v4
	v_lshlrev_b64 v[0:1], 10, v[4:5]
	v_add_u32_e32 v8, s3, v4
	v_lshl_add_u64 v[0:1], v[92:93], 0, v[0:1]
	v_ashrrev_i32_e32 v9, 31, v8
	s_waitcnt lgkmcnt(0)
	s_barrier
; #define SCAN_LOAD(j) do { \
;         _Pragma("unroll") for (int i = 0; i < 4; ++i) { const size_t r = (size_t)(rfirst + rstep * ((j) * 128 + sp * 4 + i)); \
;             kreg[i] = *(const u32x4*)(K0 + r * 512 + h * 128 + ch * 8); vreg[i] = *(const u32x4*)(P0 + r * LDP + 1536 + h * 128 + ch * 8); } \
;         } while (0)
; template <int SPLIT> __device__ __forceinline__ void scan_item(const Params& p, unsigned char* smem, const int item, const int vh) {
;     ...
;             SCAN_LOAD(jn);
;             __builtin_amdgcn_sched_barrier(0);
;             const int l = wid * 16 + li;
;             const float Ml = M_s[l], gl = g_s[l];
;             f32x4 acc[8];
; #pragma unroll
;             for (int nb = 0; nb < 8; ++nb) acc[nb] = (f32x4){0.f, 0.f, 0.f, 0.f};
;             mm16<8>(acc, KP, qf, lane);
	global_load_dwordx4 v[44:47], v[0:1], off
	v_mad_i64_i32 v[0:1], s[4:5], v4, s88, v[108:109]
	v_lshlrev_b64 v[4:5], 10, v[8:9]
	v_add_u32_e32 v16, s3, v8
	v_lshl_add_u64 v[4:5], v[92:93], 0, v[4:5]
	v_ashrrev_i32_e32 v17, 31, v16
	global_load_dwordx4 v[40:43], v[4:5], off
	v_mad_i64_i32 v[4:5], s[4:5], v8, s88, v[108:109]
	v_lshlrev_b64 v[8:9], 10, v[16:17]
	v_lshl_add_u64 v[8:9], v[92:93], 0, v[8:9]
	global_load_dwordx4 v[36:39], v[8:9], off
	v_mad_i64_i32 v[8:9], s[4:5], v16, s88, v[108:109]
	v_add_u32_e32 v16, s3, v16
	v_ashrrev_i32_e32 v17, 31, v16
	v_lshlrev_b64 v[18:19], 10, v[16:17]
	v_lshl_add_u64 v[18:19], v[92:93], 0, v[18:19]
	v_mad_i64_i32 v[16:17], s[4:5], v16, s88, v[108:109]
	global_load_dwordx4 v[0:3], v[0:1], off offset:3072
	v_sub_f32_e32 v81, v80, v81
	global_load_dwordx4 v[4:7], v[4:5], off offset:3072
	v_mul_f32_e32 v81, 0x3fb8aa3b, v81
	global_load_dwordx4 v[8:11], v[8:9], off offset:3072
	v_exp_f32_e32 v112, v81
	global_load_dwordx4 v[32:35], v[18:19], off
	s_nop 0
	global_load_dwordx4 v[16:19], v[16:17], off offset:3072
	v_add_u32_e32 v81, 0, v125
	ds_read_b128 v[82:85], v81
	ds_read_b128 v[86:89], v81 offset:4096
	ds_read_b32 v171, v123
	ds_read_b128 v[164:167], v81 offset:8192
	ds_read_b128 v[172:175], v81 offset:12288
	ds_read_b32 v177, v122
	s_waitcnt vmcnt(11) lgkmcnt(5)
	v_mfma_f32_16x16x32_bf16 v[82:85], v[82:85], v[28:31], 0
	s_waitcnt lgkmcnt(4)
	v_mfma_f32_16x16x32_bf16 v[86:89], v[86:89], v[28:31], 0
	s_waitcnt lgkmcnt(2)
	v_mfma_f32_16x16x32_bf16 v[166:169], v[164:167], v[28:31], 0
	s_waitcnt lgkmcnt(1)
	v_mfma_f32_16x16x32_bf16 v[172:175], v[172:175], v[28:31], 0
	ds_read_b128 v[178:181], v81 offset:16384
	ds_read_b128 v[182:185], v81 offset:20480
	ds_read_b128 v[186:189], v81 offset:24576
	ds_read_b128 v[190:193], v81 offset:28672
	s_waitcnt lgkmcnt(3)
	v_mfma_f32_16x16x32_bf16 v[178:181], v[178:181], v[28:31], 0
	s_waitcnt lgkmcnt(2)
	v_mfma_f32_16x16x32_bf16 v[182:185], v[182:185], v[28:31], 0
	s_waitcnt lgkmcnt(1)
	v_mfma_f32_16x16x32_bf16 v[186:189], v[186:189], v[28:31], 0
	s_waitcnt lgkmcnt(0)
	v_mfma_f32_16x16x32_bf16 v[190:193], v[190:193], v[28:31], 0
	v_add_u32_e32 v165, 0, v127
	ds_read_b128 v[194:197], v165
	s_waitcnt vmcnt(10) lgkmcnt(0)
	v_mfma_f32_16x16x32_bf16 v[82:85], v[194:197], v[24:27], v[82:85]
	ds_read_b128 v[194:197], v165 offset:4096
	s_waitcnt lgkmcnt(0)
	v_mfma_f32_16x16x32_bf16 v[86:89], v[194:197], v[24:27], v[86:89]
	ds_read_b128 v[194:197], v165 offset:8192
	s_waitcnt lgkmcnt(0)
	v_mfma_f32_16x16x32_bf16 v[194:197], v[194:197], v[24:27], v[166:169]
	ds_read_b128 v[218:221], v165 offset:12288
	ds_read_b128 v[222:225], v165 offset:16384
	ds_read_b128 v[226:229], v165 offset:20480
	ds_read_b128 v[230:233], v165 offset:24576
	ds_read_b128 v[234:237], v165 offset:28672
	s_nop 2
	v_add_u32_e32 v242, 0, v129
	ds_read_b128 v[238:241], v242
	s_waitcnt lgkmcnt(5)
	v_mfma_f32_16x16x32_bf16 v[172:175], v[218:221], v[24:27], v[172:175]
	ds_read_b128 v[218:221], v242 offset:4096
	s_waitcnt lgkmcnt(5)
	v_mfma_f32_16x16x32_bf16 v[178:181], v[222:225], v[24:27], v[178:181]
	ds_read_b128 v[222:225], v242 offset:8192
	s_waitcnt lgkmcnt(5)
	v_mfma_f32_16x16x32_bf16 v[182:185], v[226:229], v[24:27], v[182:185]
	ds_read_b128 v[226:229], v242 offset:12288
	s_waitcnt lgkmcnt(5)
	v_mfma_f32_16x16x32_bf16 v[186:189], v[230:233], v[24:27], v[186:189]
	ds_read_b128 v[230:233], v242 offset:16384
	s_waitcnt lgkmcnt(5)
	v_mfma_f32_16x16x32_bf16 v[190:193], v[234:237], v[24:27], v[190:193]
	v_add_u32_e32 v166, 0, v129
	ds_read_b128 v[234:237], v242 offset:20480
	s_waitcnt vmcnt(9) lgkmcnt(5)
	v_mfma_f32_16x16x32_bf16 v[82:85], v[238:241], v[20:23], v[82:85]
	ds_read_b128 v[238:241], v242 offset:24576
	s_waitcnt lgkmcnt(5)
	v_mfma_f32_16x16x32_bf16 v[86:89], v[218:221], v[20:23], v[86:89]
	ds_read_b128 v[218:221], v242 offset:28672
	s_waitcnt lgkmcnt(5)
	v_mfma_f32_16x16x32_bf16 v[194:197], v[222:225], v[20:23], v[194:197]
	v_add_u32_e32 v243, 0, v131
	ds_read_b128 v[222:225], v243
	s_waitcnt lgkmcnt(5)
	v_mfma_f32_16x16x32_bf16 v[172:175], v[226:229], v[20:23], v[172:175]
	ds_read_b128 v[226:229], v243 offset:4096
	s_waitcnt lgkmcnt(5)
	v_mfma_f32_16x16x32_bf16 v[178:181], v[230:233], v[20:23], v[178:181]
	ds_read_b128 v[230:233], v243 offset:8192
	s_waitcnt lgkmcnt(5)
	v_mfma_f32_16x16x32_bf16 v[182:185], v[234:237], v[20:23], v[182:185]
	ds_read_b128 v[234:237], v243 offset:12288
	s_waitcnt lgkmcnt(5)
	v_mfma_f32_16x16x32_bf16 v[186:189], v[238:241], v[20:23], v[186:189]
	ds_read_b128 v[238:241], v243 offset:16384
	s_waitcnt lgkmcnt(5)
	v_mfma_f32_16x16x32_bf16 v[190:193], v[218:221], v[20:23], v[190:193]
	v_add_u32_e32 v167, 0, v131
	ds_read_b128 v[218:221], v243 offset:20480
	s_waitcnt vmcnt(8) lgkmcnt(5)
	v_mfma_f32_16x16x32_bf16 v[82:85], v[222:225], v[12:15], v[82:85]
	ds_read_b128 v[222:225], v243 offset:24576
	s_waitcnt lgkmcnt(5)
	v_mfma_f32_16x16x32_bf16 v[86:89], v[226:229], v[12:15], v[86:89]
	ds_read_b128 v[226:229], v243 offset:28672
	s_waitcnt lgkmcnt(5)
	v_mfma_f32_16x16x32_bf16 v[194:197], v[230:233], v[12:15], v[194:197]
	s_nop 0
	s_waitcnt lgkmcnt(4)
	v_mfma_f32_16x16x32_bf16 v[172:175], v[234:237], v[12:15], v[172:175]
	s_nop 0
	s_waitcnt lgkmcnt(3)
	v_mfma_f32_16x16x32_bf16 v[178:181], v[238:241], v[12:15], v[178:181]
	s_nop 0
	s_waitcnt lgkmcnt(2)
	v_mfma_f32_16x16x32_bf16 v[182:185], v[218:221], v[12:15], v[182:185]
	s_nop 0
	s_waitcnt lgkmcnt(1)
	v_mfma_f32_16x16x32_bf16 v[186:189], v[222:225], v[12:15], v[186:189]
	s_nop 0
	s_waitcnt lgkmcnt(0)
	v_mfma_f32_16x16x32_bf16 v[190:193], v[226:229], v[12:15], v[190:193]
	v_mov_b32_e32 v90, s6
	ds_read_b32 v90, v90
	s_waitcnt lgkmcnt(0)
; __device__ __forceinline__ unsigned cvt_pk(float lo, float hi) { unsigned r; asm volatile("v_cvt_pk_bf16_f32 %0, %1, %2" : "=v"(r) : "v"(lo), "v"(hi)); return r; }
; __device__ __forceinline__ float bflo(unsigned w) { return __uint_as_float(w << 16); }
; __device__ __forceinline__ float bfhi(unsigned w) { return __uint_as_float(w & 0xffff0000u); }
; template <int SPLIT> __device__ __forceinline__ void scan_item(const Params& p, unsigned char* smem, const int item, const int vh) {
;     ...
;             float rs = 0.f; u32x2 pp[8];
;             const float rowf = __expf(fminf(sc[1] - Ml, 80.f));
; #pragma unroll
;             for (int nb = 0; nb < 8; ++nb) { float pv[4];
; #pragma unroll
;                 for (int jj = 0; jj < 4; ++jj) { const int s = nb * 16 + kq * 4 + jj; pv[jj] = (s <= l) ? acc[nb][jj] * rowf : 0.f; rs += pv[jj]; }
;                 pp[nb].x = cvt_pk(pv[0], pv[1]); pp[nb].y = cvt_pk(pv[2], pv[3]); }
;             __builtin_amdgcn_sched_barrier(0);
;             float nq = 0.f;
; #pragma unroll
;             for (int ks = 0; ks < 4; ++ks) { const f32x4 n0 = *(const f32x4*)(n_s + ks * 32 + kq * 8), n1 = *(const f32x4*)(n_s + ks * 32 + kq * 8 + 4);
;                 const u32x4 qw = *(const u32x4*)&qf[ks];
;                 nq += bflo(qw.x) * n0[0] + bfhi(qw.x) * n0[1] + bflo(qw.y) * n0[2] + bfhi(qw.y) * n0[3] + bflo(qw.z) * n1[0] + bfhi(qw.z) * n1[1] + bflo(qw.w) * n1[2] + bfhi(qw.w) * n1[3]; }
	v_sub_f32_e32 v90, v90, v177
	v_min_f32_e32 v90, 0x42a00000, v90
	v_mul_f32_e32 v90, 0x3fb8aa3b, v90
	v_exp_f32_e32 v164, v90
	s_nop 0
	v_mul_f32_e32 v82, v82, v164
	v_mul_f32_e32 v83, v83, v164
	v_cndmask_b32_e64 v82, v82, 0, s[10:11]
	v_mul_f32_e32 v84, v84, v164
	v_cndmask_b32_e64 v83, 0, v83, s[12:13]
	v_add_f32_e32 v90, 0, v82
	v_mul_f32_e32 v85, v85, v164
	v_cndmask_b32_e64 v84, v84, 0, s[14:15]
	v_cvt_pk_bf16_f32 v82, v82, v83
	v_add_f32_e32 v83, v83, v90
	v_cndmask_b32_e64 v85, v85, 0, s[16:17]
	v_add_f32_e32 v83, v84, v83
	v_add_f32_e32 v90, v85, v83
	v_cvt_pk_bf16_f32 v83, v84, v85
	v_mul_f32_e32 v84, v86, v164
	v_cndmask_b32_e64 v84, v84, 0, s[18:19]
	v_mul_f32_e32 v86, v87, v164
	v_add_f32_e32 v85, v84, v90
	v_cndmask_b32_e64 v86, v86, 0, s[20:21]
	v_mul_f32_e32 v87, v88, v164
	v_add_f32_e32 v85, v86, v85
	v_cndmask_b32_e64 v87, v87, 0, s[22:23]
	v_mul_f32_e32 v88, v89, v164
	v_add_f32_e32 v85, v87, v85
	v_cndmask_b32_e64 v88, v88, 0, s[24:25]
	v_cvt_pk_bf16_f32 v84, v84, v86
	v_mul_f32_e32 v86, v194, v164
	v_add_f32_e32 v89, v88, v85
	v_cvt_pk_bf16_f32 v85, v87, v88
	v_cndmask_b32_e64 v86, v86, 0, s[26:27]
	v_mul_f32_e32 v88, v195, v164
	v_add_f32_e32 v87, v86, v89
	v_cndmask_b32_e64 v88, v88, 0, s[28:29]
	v_mul_f32_e32 v89, v196, v164
	v_add_f32_e32 v87, v88, v87
	v_cndmask_b32_e64 v89, v89, 0, s[30:31]
	v_mul_f32_e32 v90, v197, v164
	v_add_f32_e32 v87, v89, v87
	v_cndmask_b32_e64 v90, v90, 0, s[34:35]
	v_cvt_pk_bf16_f32 v86, v86, v88
	v_mul_f32_e32 v88, v172, v164
	v_add_f32_e32 v91, v90, v87
	v_cvt_pk_bf16_f32 v87, v89, v90
	v_cndmask_b32_e64 v88, v88, 0, s[36:37]
	v_mul_f32_e32 v90, v173, v164
	v_add_f32_e32 v89, v88, v91
	v_cndmask_b32_e64 v90, v90, 0, s[38:39]
	v_mul_f32_e32 v91, v174, v164
	v_add_f32_e32 v89, v90, v89
	v_cndmask_b32_e64 v91, v91, 0, s[40:41]
	v_mul_f32_e32 v95, v175, v164
	v_add_f32_e32 v89, v91, v89
	v_cndmask_b32_e64 v95, v95, 0, s[42:43]
	v_cvt_pk_bf16_f32 v88, v88, v90
	v_mul_f32_e32 v90, v178, v164
	v_add_f32_e32 v168, v95, v89
	v_cvt_pk_bf16_f32 v89, v91, v95
	v_cndmask_b32_e64 v90, v90, 0, s[44:45]
	v_mul_f32_e32 v95, v179, v164
	v_add_f32_e32 v91, v90, v168
	v_cndmask_b32_e64 v95, v95, 0, s[46:47]
	v_mul_f32_e32 v168, v180, v164
	v_add_f32_e32 v91, v95, v91
	v_cndmask_b32_e64 v168, v168, 0, s[48:49]
	v_mul_f32_e32 v169, v181, v164
	v_add_f32_e32 v91, v168, v91
	v_cndmask_b32_e64 v169, v169, 0, s[50:51]
	v_cvt_pk_bf16_f32 v90, v90, v95
	v_mul_f32_e32 v95, v182, v164
	v_add_f32_e32 v172, v169, v91
	v_cvt_pk_bf16_f32 v91, v168, v169
	v_cndmask_b32_e64 v95, v95, 0, s[52:53]
	v_mul_f32_e32 v168, v183, v164
	v_add_f32_e32 v169, v95, v172
	v_cndmask_b32_e64 v183, v168, 0, s[54:55]
	v_cvt_pk_bf16_f32 v198, v95, v183
	v_mul_f32_e32 v95, v186, v164
	v_mul_f32_e32 v168, v184, v164
	v_cndmask_b32_e64 v201, v95, 0, s[60:61]
	v_mul_f32_e32 v95, v187, v164
	v_cndmask_b32_e64 v195, v168, 0, s[56:57]
	v_mul_f32_e32 v168, v185, v164
	v_cndmask_b32_e64 v203, v95, 0, s[62:63]
	v_mul_f32_e32 v95, v188, v164
	v_cndmask_b32_e64 v197, v168, 0, s[58:59]
	v_cndmask_b32_e64 v205, v95, 0, s[64:65]
	v_mul_f32_e32 v95, v189, v164
	v_mul_f32_e32 v168, v191, v164
	v_cndmask_b32_e64 v207, v95, 0, s[66:67]
	v_mul_f32_e32 v95, v190, v164
	v_cndmask_b32_e64 v214, v168, 0, s[70:71]
	v_mul_f32_e32 v168, v192, v164
	v_mul_f32_e32 v164, v193, v164
	v_cvt_pk_bf16_f32 v199, v195, v197
	v_cvt_pk_bf16_f32 v208, v201, v203
	v_cvt_pk_bf16_f32 v209, v205, v207
	v_cndmask_b32_e64 v95, v95, 0, s[68:69]
	v_cndmask_b32_e64 v215, v168, 0, s[72:73]
	v_cndmask_b32_e64 v216, v164, 0, s[74:75]
	v_cvt_pk_bf16_f32 v190, v95, v214
	v_cvt_pk_bf16_f32 v191, v215, v216
	ds_read_b128 v[172:175], v158
	ds_read_b128 v[178:181], v158 offset:16
	v_lshlrev_b32_e32 v164, 16, v28
	v_and_b32_e32 v168, 0xffff0000, v28
	v_and_b32_e32 v187, 0xffff0000, v20
	s_waitcnt lgkmcnt(1)
	v_mul_f32_e32 v182, v172, v164
	v_lshlrev_b32_e32 v164, 16, v29
	v_mul_f32_e32 v194, v174, v164
	v_and_b32_e32 v164, 0xffff0000, v29
	v_mul_f32_e32 v168, v173, v168
	v_mul_f32_e32 v196, v175, v164
	v_lshlrev_b32_e32 v164, 16, v30
	ds_read_b128 v[172:175], v158 offset:128
	s_waitcnt lgkmcnt(1)
	v_mul_f32_e32 v200, v178, v164
	v_and_b32_e32 v164, 0xffff0000, v30
	v_mul_f32_e32 v202, v179, v164
	v_lshlrev_b32_e32 v164, 16, v31
	v_mul_f32_e32 v204, v180, v164
	v_and_b32_e32 v164, 0xffff0000, v31
	v_pk_add_f32 v[168:169], v[182:183], v[168:169]
	v_mul_f32_e32 v206, v181, v164
	ds_read_b128 v[178:181], v158 offset:144
	v_and_b32_e32 v183, 0xffff0000, v24
	v_lshlrev_b32_e32 v182, 16, v24
	s_waitcnt lgkmcnt(1)
	v_mul_f32_e32 v164, v173, v183
	v_pk_fma_f32 v[172:173], v[172:173], v[182:183], v[164:165] op_sel_hi:[1,1,0]
	v_and_b32_e32 v183, 0xffff0000, v25
	v_lshlrev_b32_e32 v182, 16, v25
	v_pk_fma_f32 v[172:173], v[174:175], v[182:183], v[172:173]
	v_mul_f32_e32 v164, v175, v183
	v_pk_add_f32 v[172:173], v[164:165], v[172:173] op_sel_hi:[0,1]
	v_and_b32_e32 v175, 0xffff0000, v26
	v_lshlrev_b32_e32 v174, 16, v26
	s_waitcnt lgkmcnt(0)
	v_pk_fma_f32 v[172:173], v[178:179], v[174:175], v[172:173]
	v_mul_f32_e32 v164, v179, v175
	v_pk_add_f32 v[178:179], v[164:165], v[172:173] op_sel_hi:[0,1]
	ds_read_b128 v[172:175], v158 offset:256
	ds_read_b128 v[182:185], v158 offset:272
	v_lshlrev_b32_e32 v186, 16, v20
	v_and_b32_e32 v213, 0xffff0000, v12
	v_lshlrev_b32_e32 v212, 16, v12
	s_waitcnt lgkmcnt(1)
	v_mul_f32_e32 v164, v173, v187
	v_pk_fma_f32 v[172:173], v[172:173], v[186:187], v[164:165] op_sel_hi:[1,1,0]
	v_and_b32_e32 v187, 0xffff0000, v21
	v_lshlrev_b32_e32 v186, 16, v21
	v_pk_fma_f32 v[172:173], v[174:175], v[186:187], v[172:173]
	v_mul_f32_e32 v164, v175, v187
	v_pk_add_f32 v[172:173], v[164:165], v[172:173] op_sel_hi:[0,1]
	v_and_b32_e32 v175, 0xffff0000, v22
	v_lshlrev_b32_e32 v174, 16, v22
	s_waitcnt lgkmcnt(0)
; template <int SPLIT> __device__ __forceinline__ void scan_item(const Params& p, unsigned char* smem, const int item, const int vh) {
;     ...
;             rs += __shfl_xor(rs, 16); rs += __shfl_xor(rs, 32); nq += __shfl_xor(nq, 16); nq += __shfl_xor(nq, 32);
;             const float exl = __expf(m_old - Ml);
;             const float den = rs + exl * nq;
;             const float hinv = __builtin_amdgcn_rcpf(fmaxf(fabsf(den), __expf(-(gl + Ml))));
;             __syncthreads();
; #pragma unroll
;             for (int nb = 0; nb < 8; ++nb) *(u32x2*)(KP + swz(l, nb * 2 + (kq >> 1)) + (kq & 1) * 8) = pp[nb];
;             f32x4 acc2[NBV];
; #pragma unroll
;             for (int nb = 0; nb < NBV; ++nb) acc2[nb] = (f32x4){0.f, 0.f, 0.f, 0.f};
;             __builtin_amdgcn_sched_barrier(0);
;             mm16<NBV>(acc2, CS + vh * 16384, qf, lane);
;             __builtin_amdgcn_sched_barrier(0);
	v_pk_fma_f32 v[172:173], v[182:183], v[174:175], v[172:173]
	v_mul_f32_e32 v164, v183, v175
	v_pk_add_f32 v[182:183], v[164:165], v[172:173] op_sel_hi:[0,1]
	ds_read_b128 v[172:175], v158 offset:384
	ds_read_b128 v[186:189], v158 offset:400
	v_pk_add_f32 v[168:169], v[194:195], v[168:169]
	v_and_b32_e32 v193, 0xffff0000, v27
	v_pk_add_f32 v[168:169], v[196:197], v[168:169]
	s_waitcnt lgkmcnt(1)
	v_mul_f32_e32 v164, v173, v213
	v_pk_fma_f32 v[172:173], v[172:173], v[212:213], v[164:165] op_sel_hi:[1,1,0]
	v_and_b32_e32 v213, 0xffff0000, v13
	v_lshlrev_b32_e32 v212, 16, v13
	v_pk_fma_f32 v[172:173], v[174:175], v[212:213], v[172:173]
	v_mul_f32_e32 v164, v175, v213
	v_pk_add_f32 v[172:173], v[164:165], v[172:173] op_sel_hi:[0,1]
	v_and_b32_e32 v175, 0xffff0000, v14
	v_lshlrev_b32_e32 v174, 16, v14
	s_waitcnt lgkmcnt(0)
	v_pk_fma_f32 v[172:173], v[186:187], v[174:175], v[172:173]
	v_mul_f32_e32 v164, v187, v175
	v_pk_add_f32 v[172:173], v[164:165], v[172:173] op_sel_hi:[0,1]
	v_and_b32_e32 v175, 0xffff0000, v15
	v_lshlrev_b32_e32 v174, 16, v15
	v_pk_add_f32 v[168:169], v[200:201], v[168:169]
	v_lshlrev_b32_e32 v192, 16, v27
	v_pk_fma_f32 v[172:173], v[188:189], v[174:175], v[172:173]
	v_and_b32_e32 v174, 64, v163
	v_pk_add_f32 v[168:169], v[202:203], v[168:169]
	v_pk_fma_f32 v[178:179], v[180:181], v[192:193], v[178:179]
	v_add_u32_e32 v180, 64, v174
	v_pk_add_f32 v[168:169], v[204:205], v[168:169]
	v_mul_f32_e32 v174, v181, v193
	v_and_b32_e32 v211, 0xffff0000, v23
	v_lshlrev_b32_e32 v210, 16, v23
	v_pk_add_f32 v[168:169], v[206:207], v[168:169]
	v_pk_add_f32 v[178:179], v[174:175], v[178:179] op_sel_hi:[0,1]
	v_pk_fma_f32 v[182:183], v[184:185], v[210:211], v[182:183]
	v_pk_add_f32 v[168:169], v[94:95], v[168:169]
	v_mov_b32_e32 v179, v214
	v_mul_f32_e32 v174, v185, v211
	v_xor_b32_e32 v164, 16, v163
	v_pk_add_f32 v[168:169], v[178:179], v[168:169]
	v_pk_add_f32 v[178:179], v[174:175], v[182:183] op_sel_hi:[0,1]
	v_mul_f32_e32 v174, v189, v175
	v_cmp_lt_i32_e32 vcc, v164, v180
	v_mov_b32_e32 v179, v215
	v_pk_add_f32 v[172:173], v[174:175], v[172:173] op_sel_hi:[0,1]
	v_cndmask_b32_e32 v164, v163, v164, vcc
	v_pk_add_f32 v[168:169], v[178:179], v[168:169]
	v_mov_b32_e32 v173, v216
	v_lshlrev_b32_e32 v164, 2, v164
	v_pk_add_f32 v[168:169], v[172:173], v[168:169]
	ds_bpermute_b32 v173, v164, v169
	ds_bpermute_b32 v172, v164, v168
	v_xor_b32_e32 v95, 32, v163
	v_cmp_lt_i32_e32 vcc, v95, v180
	v_sub_f32_e32 v80, v80, v177
	v_mul_f32_e32 v80, 0x3fb8aa3b, v80
	v_cndmask_b32_e32 v95, v163, v95, vcc
	v_lshlrev_b32_e32 v95, 2, v95
	s_waitcnt lgkmcnt(0)
	v_pk_add_f32 v[168:169], v[168:169], v[172:173]
	ds_bpermute_b32 v173, v95, v169
	ds_bpermute_b32 v172, v95, v168
	v_add_f32_e32 v171, v177, v171
	v_exp_f32_e32 v80, v80
	v_mul_f32_e32 v171, 0xbfb8aa3b, v171
	v_exp_f32_e32 v171, v171
	s_waitcnt lgkmcnt(0)
	v_pk_add_f32 v[168:169], v[168:169], v[172:173]
	s_nop 0
	v_fmac_f32_e32 v169, v80, v168
	v_max_f32_e64 v168, |v169|, v171
	v_add_u32_e32 v169, v132, v144
	s_barrier
	ds_write_b64 v169, v[82:83]
	v_add_u32_e32 v82, v132, v145
	ds_write_b64 v82, v[84:85]
	v_add_u32_e32 v82, v132, v146
	ds_write_b64 v82, v[86:87]
	v_add_u32_e32 v82, v132, v147
	ds_write_b64 v82, v[88:89]
	v_add_u32_e32 v82, v132, v148
	ds_write_b64 v82, v[90:91]
	v_add_u32_e32 v82, v132, v149
	ds_write_b64 v82, v[198:199]
	v_add_u32_e32 v82, v132, v150
	ds_write_b64 v82, v[208:209]
	v_add_u32_e32 v82, v132, v151
	ds_write_b64 v82, v[190:191]
	v_add_u32_e32 v90, s92, v125
	ds_read_b128 v[82:85], v90
	ds_read_b128 v[86:89], v90 offset:4096
	ds_read_b128 v[172:175], v90 offset:8192
	ds_read_b128 v[178:181], v90 offset:12288
	s_waitcnt lgkmcnt(3)
	v_mfma_f32_16x16x32_bf16 v[82:85], v[82:85], v[28:31], 0
	s_waitcnt lgkmcnt(2)
	v_mfma_f32_16x16x32_bf16 v[86:89], v[86:89], v[28:31], 0
	s_waitcnt lgkmcnt(1)
	v_mfma_f32_16x16x32_bf16 v[172:175], v[172:175], v[28:31], 0
	s_waitcnt lgkmcnt(0)
	v_mfma_f32_16x16x32_bf16 v[178:181], v[178:181], v[28:31], 0
	ds_read_b128 v[182:185], v90 offset:16384
	ds_read_b128 v[186:189], v90 offset:20480
	ds_read_b128 v[190:193], v90 offset:24576
	ds_read_b128 v[194:197], v90 offset:28672
	s_waitcnt lgkmcnt(3)
	v_mfma_f32_16x16x32_bf16 v[182:185], v[182:185], v[28:31], 0
	s_waitcnt lgkmcnt(2)
	v_mfma_f32_16x16x32_bf16 v[186:189], v[186:189], v[28:31], 0
	s_waitcnt lgkmcnt(1)
	v_mfma_f32_16x16x32_bf16 v[190:193], v[190:193], v[28:31], 0
	s_waitcnt lgkmcnt(0)
	v_mfma_f32_16x16x32_bf16 v[28:31], v[194:197], v[28:31], 0
	v_add_u32_e32 v244, s92, v127
	ds_read_b128 v[218:221], v244
	ds_read_b128 v[222:225], v244 offset:4096
	ds_read_b128 v[226:229], v244 offset:8192
	ds_read_b128 v[230:233], v244 offset:12288
	ds_read_b128 v[234:237], v244 offset:16384
	v_add_u32_e32 v90, s92, v127
	ds_read_b128 v[238:241], v244 offset:20480
	s_waitcnt lgkmcnt(5)
	v_mfma_f32_16x16x32_bf16 v[82:85], v[218:221], v[24:27], v[82:85]
	ds_read_b128 v[218:221], v244 offset:24576
	s_waitcnt lgkmcnt(5)
	v_mfma_f32_16x16x32_bf16 v[86:89], v[222:225], v[24:27], v[86:89]
	ds_read_b128 v[222:225], v244 offset:28672
	s_waitcnt lgkmcnt(5)
	v_mfma_f32_16x16x32_bf16 v[172:175], v[226:229], v[24:27], v[172:175]
	s_nop 0
	s_waitcnt lgkmcnt(4)
	v_mfma_f32_16x16x32_bf16 v[178:181], v[230:233], v[24:27], v[178:181]
	s_nop 0
	s_waitcnt lgkmcnt(3)
	v_mfma_f32_16x16x32_bf16 v[182:185], v[234:237], v[24:27], v[182:185]
	s_nop 0
	s_waitcnt lgkmcnt(2)
	v_mfma_f32_16x16x32_bf16 v[186:189], v[238:241], v[24:27], v[186:189]
	s_nop 0
	s_waitcnt lgkmcnt(1)
	v_mfma_f32_16x16x32_bf16 v[190:193], v[218:221], v[24:27], v[190:193]
	s_nop 0
	s_waitcnt lgkmcnt(0)
; #define Q_LOAD(j) do { const size_t r = (size_t)(rfirst + rstep * ((j) * 128 + wid * 16 + li)); \
;           _Pragma("unroll") for (int ks = 0; ks < 4; ++ks) qf[ks] = *(const bf16x8*)(Q0 + r * 512 + h * 128 + ks * 32 + kq * 8); } while (0)
; template <int SPLIT> __device__ __forceinline__ void scan_item(const Params& p, unsigned char* smem, const int item, const int vh) {
;     ...
;             mm16<NBV>(acc2, CS + vh * 16384, qf, lane);
;             __builtin_amdgcn_sched_barrier(0);
;             Q_LOAD(jn);
; #pragma unroll
;             for (int nb = 0; nb < NBV; ++nb) acc2[nb] *= exl;
;             __builtin_amdgcn_sched_barrier(0);
;             { bf16x8 pf[4]; ldfrag(pf, KP, wid, lane); mm16<NBV>(acc2, VT + vh * 16384, pf, lane); }
	v_mfma_f32_16x16x32_bf16 v[24:27], v[222:225], v[24:27], v[28:31]
	v_add_u32_e32 v90, s92, v129
	s_nop 1
	ds_read_b128 v[28:31], v90
	s_waitcnt lgkmcnt(0)
	v_mfma_f32_16x16x32_bf16 v[28:31], v[28:31], v[20:23], v[82:85]
	s_nop 2
	ds_read_b128 v[82:85], v90 offset:4096
	s_waitcnt lgkmcnt(0)
	v_mfma_f32_16x16x32_bf16 v[82:85], v[82:85], v[20:23], v[86:89]
	s_nop 2
	ds_read_b128 v[86:89], v90 offset:8192
	s_waitcnt lgkmcnt(0)
	v_mfma_f32_16x16x32_bf16 v[86:89], v[86:89], v[20:23], v[172:175]
	s_nop 2
	ds_read_b128 v[172:175], v90 offset:12288
	s_waitcnt lgkmcnt(0)
	v_mfma_f32_16x16x32_bf16 v[172:175], v[172:175], v[20:23], v[178:181]
	s_nop 2
	ds_read_b128 v[178:181], v90 offset:16384
	s_waitcnt lgkmcnt(0)
	v_mfma_f32_16x16x32_bf16 v[178:181], v[178:181], v[20:23], v[182:185]
	s_nop 2
	ds_read_b128 v[182:185], v90 offset:20480
	s_waitcnt lgkmcnt(0)
	v_mfma_f32_16x16x32_bf16 v[182:185], v[182:185], v[20:23], v[186:189]
	s_nop 2
	ds_read_b128 v[186:189], v90 offset:24576
	s_waitcnt lgkmcnt(0)
	v_mfma_f32_16x16x32_bf16 v[186:189], v[186:189], v[20:23], v[190:193]
	ds_read_b128 v[218:221], v90 offset:28672
	v_add_u32_e32 v245, s92, v131
	ds_read_b128 v[222:225], v245
	ds_read_b128 v[226:229], v245 offset:4096
	ds_read_b128 v[230:233], v245 offset:8192
	ds_read_b128 v[234:237], v245 offset:12288
	s_nop 2
	ds_read_b128 v[238:241], v245 offset:16384
	s_waitcnt lgkmcnt(5)
	v_mfma_f32_16x16x32_bf16 v[20:23], v[218:221], v[20:23], v[24:27]
	v_add_u32_e32 v90, s92, v131
	s_nop 1
	ds_read_b128 v[218:221], v245 offset:20480
	s_waitcnt lgkmcnt(5)
	v_mfma_f32_16x16x32_bf16 v[190:193], v[222:225], v[12:15], v[28:31]
	ds_read_b128 v[222:225], v245 offset:24576
	s_waitcnt lgkmcnt(5)
	v_mfma_f32_16x16x32_bf16 v[82:85], v[226:229], v[12:15], v[82:85]
	ds_read_b128 v[226:229], v245 offset:28672
	s_waitcnt lgkmcnt(5)
	v_mfma_f32_16x16x32_bf16 v[86:89], v[230:233], v[12:15], v[86:89]
	s_nop 0
	s_waitcnt lgkmcnt(4)
	v_mfma_f32_16x16x32_bf16 v[172:175], v[234:237], v[12:15], v[172:175]
	s_nop 0
	s_waitcnt lgkmcnt(3)
	v_mfma_f32_16x16x32_bf16 v[178:181], v[238:241], v[12:15], v[178:181]
	s_nop 0
	s_waitcnt lgkmcnt(2)
	v_mfma_f32_16x16x32_bf16 v[182:185], v[218:221], v[12:15], v[182:185]
	s_nop 0
	s_waitcnt lgkmcnt(1)
	v_mfma_f32_16x16x32_bf16 v[186:189], v[222:225], v[12:15], v[186:189]
	s_nop 0
	s_waitcnt lgkmcnt(0)
	v_mfma_f32_16x16x32_bf16 v[194:197], v[226:229], v[12:15], v[20:23]
	v_add_u32_e32 v12, s0, v114
	v_mul_lo_u32 v12, v12, s3
	v_add_u32_e32 v12, s33, v12
	v_ashrrev_i32_e32 v13, 31, v12
	v_lshlrev_b64 v[12:13], 10, v[12:13]
	v_lshl_add_u64 v[12:13], v[104:105], 0, v[12:13]
	global_load_dwordx4 v[28:31], v[12:13], off
	global_load_dwordx4 v[24:27], v[12:13], off offset:64
	global_load_dwordx4 v[20:23], v[12:13], off offset:128
	s_nop 0
	global_load_dwordx4 v[12:15], v[12:13], off offset:192
	v_pk_mul_f32 v[82:83], v[80:81], v[82:83] op_sel_hi:[0,1]
	v_pk_mul_f32 v[192:193], v[80:81], v[192:193] op_sel_hi:[0,1]
	v_pk_mul_f32 v[190:191], v[80:81], v[190:191] op_sel_hi:[0,1]
	v_pk_mul_f32 v[84:85], v[80:81], v[84:85] op_sel_hi:[0,1]
	v_pk_mul_f32 v[88:89], v[80:81], v[88:89] op_sel_hi:[0,1]
	v_pk_mul_f32 v[86:87], v[80:81], v[86:87] op_sel_hi:[0,1]
	v_pk_mul_f32 v[174:175], v[80:81], v[174:175] op_sel_hi:[0,1]
	v_pk_mul_f32 v[172:173], v[80:81], v[172:173] op_sel_hi:[0,1]
	v_pk_mul_f32 v[180:181], v[80:81], v[180:181] op_sel_hi:[0,1]
	v_pk_mul_f32 v[178:179], v[80:81], v[178:179] op_sel_hi:[0,1]
	v_pk_mul_f32 v[184:185], v[80:81], v[184:185] op_sel_hi:[0,1]
	v_pk_mul_f32 v[182:183], v[80:81], v[182:183] op_sel_hi:[0,1]
	v_pk_mul_f32 v[188:189], v[80:81], v[188:189] op_sel_hi:[0,1]
	v_rcp_f32_e32 v171, v168
	v_pk_mul_f32 v[186:187], v[80:81], v[186:187] op_sel_hi:[0,1]
	v_pk_mul_f32 v[196:197], v[80:81], v[196:197] op_sel_hi:[0,1]
	v_pk_mul_f32 v[194:195], v[80:81], v[194:195] op_sel_hi:[0,1]
	ds_read_b128 v[198:201], v81 offset:32768
	ds_read_b128 v[202:205], v81 offset:36864
	ds_read_b128 v[206:209], v159
	ds_read_b128 v[210:213], v160
	s_waitcnt lgkmcnt(1)
	v_mfma_f32_16x16x32_bf16 v[190:193], v[198:201], v[206:209], v[190:193]
	ds_read_b128 v[198:201], v81 offset:40960
	v_mfma_f32_16x16x32_bf16 v[82:85], v[202:205], v[206:209], v[82:85]
	ds_read_b128 v[202:205], v81 offset:45056
	s_waitcnt lgkmcnt(1)
	v_mfma_f32_16x16x32_bf16 v[86:89], v[198:201], v[206:209], v[86:89]
	ds_read_b128 v[198:201], v161
	ds_read_b128 v[214:217], v162
	s_waitcnt lgkmcnt(2)
	v_mfma_f32_16x16x32_bf16 v[172:175], v[202:205], v[206:209], v[172:175]
	ds_read_b128 v[226:229], v81 offset:49152
	ds_read_b128 v[230:233], v81 offset:53248
	ds_read_b128 v[234:237], v81 offset:57344
	ds_read_b128 v[202:205], v81 offset:61440
	s_waitcnt lgkmcnt(3)
	v_mfma_f32_16x16x32_bf16 v[178:181], v[226:229], v[206:209], v[178:181]
	s_nop 0
	s_waitcnt lgkmcnt(2)
	v_mfma_f32_16x16x32_bf16 v[182:185], v[230:233], v[206:209], v[182:185]
	s_nop 0
	s_waitcnt lgkmcnt(1)
	v_mfma_f32_16x16x32_bf16 v[186:189], v[234:237], v[206:209], v[186:189]
	s_nop 0
	s_waitcnt lgkmcnt(0)
	v_mfma_f32_16x16x32_bf16 v[194:197], v[202:205], v[206:209], v[194:197]
	s_nop 0
	ds_read_b128 v[202:205], v165 offset:32768
	s_waitcnt lgkmcnt(0)
	v_mfma_f32_16x16x32_bf16 v[190:193], v[202:205], v[210:213], v[190:193]
	ds_read_b128 v[202:205], v165 offset:36864
	s_waitcnt lgkmcnt(0)
	v_mfma_f32_16x16x32_bf16 v[80:83], v[202:205], v[210:213], v[82:85]
	ds_read_b128 v[202:205], v165 offset:40960
	s_waitcnt lgkmcnt(0)
	v_mfma_f32_16x16x32_bf16 v[84:87], v[202:205], v[210:213], v[86:89]
	s_nop 2
	ds_read_b128 v[88:91], v165 offset:45056
	s_waitcnt lgkmcnt(0)
	v_mfma_f32_16x16x32_bf16 v[88:91], v[88:91], v[210:213], v[172:175]
	s_nop 2
	ds_read_b128 v[172:175], v165 offset:49152
	s_waitcnt lgkmcnt(0)
; __device__ __forceinline__ unsigned cvt_pk(float lo, float hi) { unsigned r; asm volatile("v_cvt_pk_bf16_f32 %0, %1, %2" : "=v"(r) : "v"(lo), "v"(hi)); return r; }
; template <int SPLIT> __device__ __forceinline__ void scan_item(const Params& p, unsigned char* smem, const int item, const int vh) {
;     ...
;             { bf16x8 pf[4]; ldfrag(pf, KP, wid, lane); mm16<NBV>(acc2, VT + vh * 16384, pf, lane); }
;             __builtin_amdgcn_sched_barrier(0);
;             { bf16_t* hp = P0 + rowl * LDP + dir * 512 + h * 128 + vh * 64 + kq * 4;
; #pragma unroll
;               for (int nb = 0; nb < NBV; ++nb) { u32x2 o; o.x = cvt_pk(acc2[nb][0] * hinv, acc2[nb][1] * hinv); o.y = cvt_pk(acc2[nb][2] * hinv, acc2[nb][3] * hinv);
;                   *(u32x2*)(hp + nb * 16) = o; } }
;             __builtin_amdgcn_sched_barrier(0);
;             float nnew;
;             { bf16x8 vf[4]; ldfrag(vf, VT, vblk, lane);
; #pragma unroll
;               for (int nb = 0; nb < NBV; ++nb) Cacc[nb] *= decay;
;               mm16<NBV>(Cacc, KT + kh * 16384, vf, lane);
	v_mfma_f32_16x16x32_bf16 v[172:175], v[172:175], v[210:213], v[178:181]
	s_nop 2
	ds_read_b128 v[178:181], v165 offset:53248
	s_waitcnt lgkmcnt(0)
	v_mfma_f32_16x16x32_bf16 v[178:181], v[178:181], v[210:213], v[182:185]
	s_nop 2
	ds_read_b128 v[182:185], v165 offset:57344
	s_waitcnt lgkmcnt(0)
	v_mfma_f32_16x16x32_bf16 v[182:185], v[182:185], v[210:213], v[186:189]
	s_nop 2
	ds_read_b128 v[186:189], v165 offset:61440
	s_waitcnt lgkmcnt(0)
	v_mfma_f32_16x16x32_bf16 v[186:189], v[186:189], v[210:213], v[194:197]
	ds_read_b128 v[218:221], v166 offset:32768
	ds_read_b128 v[222:225], v166 offset:36864
	ds_read_b128 v[226:229], v166 offset:40960
	ds_read_b128 v[230:233], v166 offset:45056
	ds_read_b128 v[234:237], v166 offset:49152
	s_nop 2
	ds_read_b128 v[238:241], v166 offset:53248
	s_waitcnt lgkmcnt(5)
	v_mfma_f32_16x16x32_bf16 v[190:193], v[218:221], v[198:201], v[190:193]
	ds_read_b128 v[218:221], v166 offset:57344
	s_waitcnt lgkmcnt(5)
	v_mfma_f32_16x16x32_bf16 v[80:83], v[222:225], v[198:201], v[80:83]
	ds_read_b128 v[222:225], v166 offset:61440
	s_waitcnt lgkmcnt(5)
	v_mfma_f32_16x16x32_bf16 v[84:87], v[226:229], v[198:201], v[84:87]
	ds_read_b128 v[226:229], v167 offset:32768
	s_waitcnt lgkmcnt(5)
	v_mfma_f32_16x16x32_bf16 v[88:91], v[230:233], v[198:201], v[88:91]
	ds_read_b128 v[230:233], v167 offset:36864
	s_waitcnt lgkmcnt(5)
	v_mfma_f32_16x16x32_bf16 v[172:175], v[234:237], v[198:201], v[172:175]
	ds_read_b128 v[234:237], v167 offset:40960
	s_waitcnt lgkmcnt(5)
	v_mfma_f32_16x16x32_bf16 v[178:181], v[238:241], v[198:201], v[178:181]
	ds_read_b128 v[238:241], v167 offset:45056
	s_waitcnt lgkmcnt(5)
	v_mfma_f32_16x16x32_bf16 v[182:185], v[218:221], v[198:201], v[182:185]
	ds_read_b128 v[218:221], v167 offset:49152
	s_waitcnt lgkmcnt(5)
	v_mfma_f32_16x16x32_bf16 v[186:189], v[222:225], v[198:201], v[186:189]
	ds_read_b128 v[222:225], v167 offset:53248
	s_waitcnt lgkmcnt(5)
	v_mfma_f32_16x16x32_bf16 v[190:193], v[226:229], v[214:217], v[190:193]
	s_nop 0
	s_waitcnt lgkmcnt(4)
	v_mfma_f32_16x16x32_bf16 v[80:83], v[230:233], v[214:217], v[80:83]
	s_nop 0
	s_waitcnt lgkmcnt(3)
	v_mfma_f32_16x16x32_bf16 v[84:87], v[234:237], v[214:217], v[84:87]
	s_nop 0
	s_waitcnt lgkmcnt(2)
	v_mfma_f32_16x16x32_bf16 v[88:91], v[238:241], v[214:217], v[88:91]
	s_nop 0
	s_waitcnt lgkmcnt(1)
	v_mfma_f32_16x16x32_bf16 v[172:175], v[218:221], v[214:217], v[172:175]
	s_nop 0
	s_waitcnt lgkmcnt(0)
	v_mfma_f32_16x16x32_bf16 v[178:181], v[222:225], v[214:217], v[178:181]
	ds_read_b128 v[194:197], v167 offset:57344
	ds_read_b128 v[166:169], v167 offset:61440
	s_waitcnt lgkmcnt(1)
	v_mfma_f32_16x16x32_bf16 v[182:185], v[194:197], v[214:217], v[182:185]
	s_waitcnt lgkmcnt(0)
	v_mfma_f32_16x16x32_bf16 v[166:169], v[166:169], v[214:217], v[186:189]
	s_nop 2
	v_mad_i64_i32 v[186:187], s[4:5], v152, s88, v[106:107]
	v_mul_f32_e32 v165, v171, v190
	v_mul_f32_e32 v177, v171, v191
	v_mul_f32_e32 v80, v171, v80
	v_mul_f32_e32 v81, v171, v81
	v_cvt_pk_bf16_f32 v188, v165, v177
	v_mul_f32_e32 v165, v171, v192
	v_mul_f32_e32 v177, v171, v193
	v_cvt_pk_bf16_f32 v189, v165, v177
	global_store_dwordx2 v[186:187], v[188:189], off
	v_cvt_pk_bf16_f32 v80, v80, v81
	v_mul_f32_e32 v81, v171, v82
	v_mul_f32_e32 v82, v171, v83
	v_cvt_pk_bf16_f32 v81, v81, v82
	global_store_dwordx2 v[186:187], v[80:81], off offset:32
	v_mul_f32_e32 v80, v171, v84
	v_mul_f32_e32 v81, v171, v85
	v_cvt_pk_bf16_f32 v80, v80, v81
	v_mul_f32_e32 v81, v171, v86
	v_mul_f32_e32 v82, v171, v87
	v_cvt_pk_bf16_f32 v81, v81, v82
	global_store_dwordx2 v[186:187], v[80:81], off offset:64
	v_mul_f32_e32 v80, v171, v88
	v_mul_f32_e32 v81, v171, v89
	v_cvt_pk_bf16_f32 v80, v80, v81
	v_mul_f32_e32 v81, v171, v90
	v_mul_f32_e32 v82, v171, v91
	v_cvt_pk_bf16_f32 v81, v81, v82
	global_store_dwordx2 v[186:187], v[80:81], off offset:96
	v_mul_f32_e32 v80, v171, v172
	v_mul_f32_e32 v81, v171, v173
	v_cvt_pk_bf16_f32 v80, v80, v81
	v_mul_f32_e32 v81, v171, v174
	v_mul_f32_e32 v82, v171, v175
	v_cvt_pk_bf16_f32 v81, v81, v82
	global_store_dwordx2 v[186:187], v[80:81], off offset:128
	v_mul_f32_e32 v80, v171, v178
	v_mul_f32_e32 v81, v171, v179
	v_cvt_pk_bf16_f32 v80, v80, v81
	v_mul_f32_e32 v81, v171, v180
	v_mul_f32_e32 v82, v171, v181
	v_cvt_pk_bf16_f32 v81, v81, v82
	global_store_dwordx2 v[186:187], v[80:81], off offset:160
	v_mul_f32_e32 v80, v171, v182
	v_mul_f32_e32 v81, v171, v183
	v_cvt_pk_bf16_f32 v80, v80, v81
	v_mul_f32_e32 v81, v171, v184
	v_mul_f32_e32 v82, v171, v185
	v_cvt_pk_bf16_f32 v81, v81, v82
	global_store_dwordx2 v[186:187], v[80:81], off offset:192
	v_mul_f32_e32 v80, v171, v166
	v_mul_f32_e32 v81, v171, v167
	v_cvt_pk_bf16_f32 v80, v80, v81
	v_mul_f32_e32 v81, v171, v168
	v_mul_f32_e32 v82, v171, v169
	v_cvt_pk_bf16_f32 v81, v81, v82
	global_store_dwordx2 v[186:187], v[80:81], off offset:224
	v_add_u32_e32 v165, s89, v125
	ds_read_b128 v[166:169], v159 offset:32768
	ds_read_b128 v[88:91], v160 offset:32768
	ds_read_b128 v[84:87], v161 offset:32768
	ds_read_b128 v[80:83], v162 offset:32768
	ds_read_b128 v[172:175], v165
	v_pk_mul_f32 v[58:59], v[58:59], v[112:113] op_sel_hi:[1,0]
	v_pk_mul_f32 v[56:57], v[56:57], v[112:113] op_sel_hi:[1,0]
	v_pk_mul_f32 v[50:51], v[50:51], v[112:113] op_sel_hi:[1,0]
	v_pk_mul_f32 v[48:49], v[48:49], v[112:113] op_sel_hi:[1,0]
	v_pk_mul_f32 v[54:55], v[54:55], v[112:113] op_sel_hi:[1,0]
	v_pk_mul_f32 v[52:53], v[52:53], v[112:113] op_sel_hi:[1,0]
	v_pk_mul_f32 v[62:63], v[62:63], v[112:113] op_sel_hi:[1,0]
	s_waitcnt lgkmcnt(0)
; template <int SPLIT> __device__ __forceinline__ void scan_item(const Params& p, unsigned char* smem, const int item, const int vh) {
;     ...
;             { bf16x8 vf[4]; ldfrag(vf, VT, vblk, lane);
; #pragma unroll
;               for (int nb = 0; nb < NBV; ++nb) Cacc[nb] *= decay;
;               mm16<NBV>(Cacc, KT + kh * 16384, vf, lane);
	v_mfma_f32_16x16x32_bf16 v[56:59], v[172:175], v[166:169], v[56:59]
	ds_read_b128 v[172:175], v165 offset:4096
	v_pk_mul_f32 v[60:61], v[60:61], v[112:113] op_sel_hi:[1,0]
	v_pk_mul_f32 v[66:67], v[66:67], v[112:113] op_sel_hi:[1,0]
	v_pk_mul_f32 v[64:65], v[64:65], v[112:113] op_sel_hi:[1,0]
	v_pk_mul_f32 v[70:71], v[70:71], v[112:113] op_sel_hi:[1,0]
	v_pk_mul_f32 v[68:69], v[68:69], v[112:113] op_sel_hi:[1,0]
	v_pk_mul_f32 v[74:75], v[74:75], v[112:113] op_sel_hi:[1,0]
	s_waitcnt lgkmcnt(0)
	v_mfma_f32_16x16x32_bf16 v[48:51], v[172:175], v[166:169], v[48:51]
	ds_read_b128 v[172:175], v165 offset:8192
	v_pk_mul_f32 v[72:73], v[72:73], v[112:113] op_sel_hi:[1,0]
	v_pk_mul_f32 v[78:79], v[78:79], v[112:113] op_sel_hi:[1,0]
	v_pk_mul_f32 v[76:77], v[76:77], v[112:113] op_sel_hi:[1,0]
	s_waitcnt lgkmcnt(0)
	v_mfma_f32_16x16x32_bf16 v[52:55], v[172:175], v[166:169], v[52:55]
	ds_read_b128 v[222:225], v165 offset:12288
	ds_read_b128 v[226:229], v165 offset:16384
	ds_read_b128 v[230:233], v165 offset:20480
	ds_read_b128 v[234:237], v165 offset:24576
	ds_read_b128 v[172:175], v165 offset:28672
	s_waitcnt lgkmcnt(4)
	v_mfma_f32_16x16x32_bf16 v[60:63], v[222:225], v[166:169], v[60:63]
	s_nop 0
	s_waitcnt lgkmcnt(3)
	v_mfma_f32_16x16x32_bf16 v[64:67], v[226:229], v[166:169], v[64:67]
	s_nop 0
	s_waitcnt lgkmcnt(2)
	v_mfma_f32_16x16x32_bf16 v[68:71], v[230:233], v[166:169], v[68:71]
	s_nop 0
	s_waitcnt lgkmcnt(1)
	v_mfma_f32_16x16x32_bf16 v[72:75], v[234:237], v[166:169], v[72:75]
	s_nop 0
	s_waitcnt lgkmcnt(0)
	v_mfma_f32_16x16x32_bf16 v[76:79], v[172:175], v[166:169], v[76:79]
	s_nop 0
	v_add_u32_e32 v165, s89, v127
	ds_read_b128 v[234:237], v165
	ds_read_b128 v[166:169], v165 offset:4096
	ds_read_b128 v[218:221], v165 offset:8192
	ds_read_b128 v[222:225], v165 offset:12288
	ds_read_b128 v[226:229], v165 offset:16384
	ds_read_b128 v[230:233], v165 offset:20480
	s_waitcnt lgkmcnt(5)
	v_mfma_f32_16x16x32_bf16 v[56:59], v[234:237], v[88:91], v[56:59]
	ds_read_b128 v[234:237], v165 offset:24576
	s_waitcnt lgkmcnt(5)
	v_mfma_f32_16x16x32_bf16 v[48:51], v[166:169], v[88:91], v[48:51]
	ds_read_b128 v[166:169], v165 offset:28672
	s_waitcnt lgkmcnt(5)
	v_mfma_f32_16x16x32_bf16 v[52:55], v[218:221], v[88:91], v[52:55]
	s_nop 0
	s_waitcnt lgkmcnt(4)
	v_mfma_f32_16x16x32_bf16 v[60:63], v[222:225], v[88:91], v[60:63]
	s_nop 0
	s_waitcnt lgkmcnt(3)
	v_mfma_f32_16x16x32_bf16 v[64:67], v[226:229], v[88:91], v[64:67]
	s_nop 0
	s_waitcnt lgkmcnt(2)
	v_mfma_f32_16x16x32_bf16 v[68:71], v[230:233], v[88:91], v[68:71]
	s_nop 0
	s_waitcnt lgkmcnt(1)
	v_mfma_f32_16x16x32_bf16 v[72:75], v[234:237], v[88:91], v[72:75]
	s_nop 0
	s_waitcnt lgkmcnt(0)
	v_mfma_f32_16x16x32_bf16 v[76:79], v[166:169], v[88:91], v[76:79]
	s_nop 0
	v_add_u32_e32 v165, s89, v129
	ds_read_b128 v[234:237], v165
	ds_read_b128 v[88:91], v165 offset:4096
	ds_read_b128 v[218:221], v165 offset:8192
	ds_read_b128 v[222:225], v165 offset:12288
	ds_read_b128 v[226:229], v165 offset:16384
	ds_read_b128 v[230:233], v165 offset:20480
	s_waitcnt lgkmcnt(5)
	v_mfma_f32_16x16x32_bf16 v[56:59], v[234:237], v[84:87], v[56:59]
	ds_read_b128 v[234:237], v165 offset:24576
	s_waitcnt lgkmcnt(5)
	v_mfma_f32_16x16x32_bf16 v[48:51], v[88:91], v[84:87], v[48:51]
	ds_read_b128 v[88:91], v165 offset:28672
	s_waitcnt lgkmcnt(5)
	v_mfma_f32_16x16x32_bf16 v[52:55], v[218:221], v[84:87], v[52:55]
	s_nop 0
	s_waitcnt lgkmcnt(4)
	v_mfma_f32_16x16x32_bf16 v[60:63], v[222:225], v[84:87], v[60:63]
	s_nop 0
	s_waitcnt lgkmcnt(3)
	v_mfma_f32_16x16x32_bf16 v[64:67], v[226:229], v[84:87], v[64:67]
	s_nop 0
	s_waitcnt lgkmcnt(2)
	v_mfma_f32_16x16x32_bf16 v[68:71], v[230:233], v[84:87], v[68:71]
	s_nop 0
	s_waitcnt lgkmcnt(1)
	v_mfma_f32_16x16x32_bf16 v[72:75], v[234:237], v[84:87], v[72:75]
	s_nop 0
	s_waitcnt lgkmcnt(0)
	v_mfma_f32_16x16x32_bf16 v[76:79], v[88:91], v[84:87], v[76:79]
	s_nop 0
	v_add_u32_e32 v88, s89, v131
	ds_read_b128 v[234:237], v88
	ds_read_b128 v[84:87], v88 offset:4096
	ds_read_b128 v[218:221], v88 offset:8192
	ds_read_b128 v[222:225], v88 offset:12288
	ds_read_b128 v[226:229], v88 offset:16384
	ds_read_b128 v[230:233], v88 offset:20480
	s_waitcnt lgkmcnt(5)
	v_mfma_f32_16x16x32_bf16 v[56:59], v[234:237], v[80:83], v[56:59]
	ds_read_b128 v[234:237], v88 offset:24576
	s_waitcnt lgkmcnt(5)
; __device__ __forceinline__ unsigned cvt_pk(float lo, float hi) { unsigned r; asm volatile("v_cvt_pk_bf16_f32 %0, %1, %2" : "=v"(r) : "v"(lo), "v"(hi)); return r; }
; __device__ __forceinline__ float bflo(unsigned w) { return __uint_as_float(w << 16); }
; __device__ __forceinline__ float bfhi(unsigned w) { return __uint_as_float(w & 0xffff0000u); }
; template <int SPLIT> __device__ __forceinline__ void scan_item(const Params& p, unsigned char* smem, const int item, const int vh) {
;     ...
;               mm16<NBV>(Cacc, KT + kh * 16384, vf, lane);
;               float part = 0.f;
; #pragma unroll
;               for (int ks = 0; ks < 4; ++ks) { const u32x4 kw = *(const u32x4*)(KT + swz(wid * 16 + li, ks * 4 + kq));
;                   part += bflo(kw.x) + bfhi(kw.x) + bflo(kw.y) + bfhi(kw.y) + bflo(kw.z) + bfhi(kw.z) + bflo(kw.w) + bfhi(kw.w); }
;               part += __shfl_xor(part, 16); part += __shfl_xor(part, 32);
;               nnew = decay * n_s[wid * 16 + li] + part; }
;             __syncthreads();
; #pragma unroll
;             for (int nb = 0; nb < NBV; ++nb) { u32x2 o; o.x = cvt_pk(Cacc[nb][0], Cacc[nb][1]); o.y = cvt_pk(Cacc[nb][2], Cacc[nb][3]);
;                 *(u32x2*)(CS + swz(vblk * 16 + li, (kh * 4 + nb) * 2 + (kq >> 1)) + (kq & 1) * 8) = o; }
;             if (kq == 0) n_s[wid * 16 + li] = nnew;
	v_mfma_f32_16x16x32_bf16 v[48:51], v[84:87], v[80:83], v[48:51]
	ds_read_b128 v[84:87], v88 offset:28672
	s_waitcnt lgkmcnt(5)
	v_mfma_f32_16x16x32_bf16 v[52:55], v[218:221], v[80:83], v[52:55]
	s_nop 0
	s_waitcnt lgkmcnt(4)
	v_mfma_f32_16x16x32_bf16 v[60:63], v[222:225], v[80:83], v[60:63]
	s_nop 0
	s_waitcnt lgkmcnt(3)
	v_mfma_f32_16x16x32_bf16 v[64:67], v[226:229], v[80:83], v[64:67]
	s_nop 0
	s_waitcnt lgkmcnt(2)
	v_mfma_f32_16x16x32_bf16 v[68:71], v[230:233], v[80:83], v[68:71]
	s_nop 0
	s_waitcnt lgkmcnt(1)
	v_mfma_f32_16x16x32_bf16 v[72:75], v[234:237], v[80:83], v[72:75]
	s_nop 0
	s_waitcnt lgkmcnt(0)
	v_mfma_f32_16x16x32_bf16 v[76:79], v[84:87], v[80:83], v[76:79]
	s_nop 0
	v_add_u32_e32 v80, v133, v124
	ds_read_b128 v[80:83], v80
	s_waitcnt lgkmcnt(0)
	v_lshlrev_b32_e32 v84, 16, v80
	v_and_b32_e32 v80, 0xffff0000, v80
	v_add_f32_e32 v80, v84, v80
	v_lshlrev_b32_e32 v84, 16, v81
	v_add_f32_e32 v80, v80, v84
	v_and_b32_e32 v81, 0xffff0000, v81
	v_add_f32_e32 v80, v80, v81
	v_lshlrev_b32_e32 v81, 16, v82
	v_add_f32_e32 v80, v80, v81
	v_and_b32_e32 v81, 0xffff0000, v82
	v_add_f32_e32 v80, v80, v81
	v_lshlrev_b32_e32 v81, 16, v83
	v_add_f32_e32 v80, v80, v81
	v_and_b32_e32 v81, 0xffff0000, v83
	v_add_f32_e32 v80, v80, v81
	v_add_f32_e32 v84, 0, v80
	v_add_u32_e32 v80, v133, v126
	ds_read_b128 v[80:83], v80
	s_waitcnt lgkmcnt(0)
	v_lshlrev_b32_e32 v85, 16, v80
	v_and_b32_e32 v80, 0xffff0000, v80
	v_add_f32_e32 v80, v85, v80
	v_lshlrev_b32_e32 v85, 16, v81
	v_add_f32_e32 v80, v80, v85
	v_and_b32_e32 v81, 0xffff0000, v81
	v_add_f32_e32 v80, v80, v81
	v_lshlrev_b32_e32 v81, 16, v82
	v_add_f32_e32 v80, v80, v81
	v_and_b32_e32 v81, 0xffff0000, v82
	v_add_f32_e32 v80, v80, v81
	v_lshlrev_b32_e32 v81, 16, v83
	v_add_f32_e32 v80, v80, v81
	v_and_b32_e32 v81, 0xffff0000, v83
	v_add_f32_e32 v80, v80, v81
	v_add_f32_e32 v84, v84, v80
	v_add_u32_e32 v80, v133, v128
	ds_read_b128 v[80:83], v80
	s_waitcnt lgkmcnt(0)
	v_lshlrev_b32_e32 v85, 16, v80
	v_and_b32_e32 v80, 0xffff0000, v80
	v_add_f32_e32 v80, v85, v80
	v_lshlrev_b32_e32 v85, 16, v81
	v_add_f32_e32 v80, v80, v85
	v_and_b32_e32 v81, 0xffff0000, v81
	v_add_f32_e32 v80, v80, v81
	v_lshlrev_b32_e32 v81, 16, v82
	v_add_f32_e32 v80, v80, v81
	v_and_b32_e32 v81, 0xffff0000, v82
	v_add_f32_e32 v80, v80, v81
	v_lshlrev_b32_e32 v81, 16, v83
	v_add_f32_e32 v80, v80, v81
	v_and_b32_e32 v81, 0xffff0000, v83
	v_add_f32_e32 v80, v80, v81
	v_add_f32_e32 v84, v84, v80
	v_add_u32_e32 v80, v133, v130
	ds_read_b128 v[80:83], v80
	s_waitcnt lgkmcnt(0)
	v_lshlrev_b32_e32 v85, 16, v80
	v_and_b32_e32 v80, 0xffff0000, v80
	v_add_f32_e32 v80, v85, v80
	v_lshlrev_b32_e32 v85, 16, v81
	v_add_f32_e32 v80, v80, v85
	v_and_b32_e32 v81, 0xffff0000, v81
	v_add_f32_e32 v80, v80, v81
	v_lshlrev_b32_e32 v81, 16, v82
	v_add_f32_e32 v80, v80, v81
	v_and_b32_e32 v81, 0xffff0000, v82
	v_add_f32_e32 v80, v80, v81
	v_lshlrev_b32_e32 v81, 16, v83
	v_add_f32_e32 v80, v80, v81
	v_and_b32_e32 v81, 0xffff0000, v83
	v_add_f32_e32 v80, v80, v81
	v_add_f32_e32 v80, v84, v80
	ds_bpermute_b32 v81, v164, v80
	v_add_u32_e32 v83, v135, v144
	ds_read_b32 v82, v134
	s_waitcnt lgkmcnt(0)
	s_barrier
	v_cvt_pk_bf16_f32 v84, v56, v57
	v_cvt_pk_bf16_f32 v85, v58, v59
	ds_write_b64 v83, v[84:85]
	v_add_u32_e32 v83, v135, v145
	v_add_f32_e32 v80, v80, v81
	v_cvt_pk_bf16_f32 v84, v48, v49
	v_cvt_pk_bf16_f32 v85, v50, v51
	ds_write_b64 v83, v[84:85]
	v_add_u32_e32 v83, v135, v146
	ds_bpermute_b32 v81, v95, v80
	v_cvt_pk_bf16_f32 v84, v52, v53
	v_cvt_pk_bf16_f32 v85, v54, v55
	ds_write_b64 v83, v[84:85]
	v_add_u32_e32 v83, v135, v147
	v_cvt_pk_bf16_f32 v84, v60, v61
	v_cvt_pk_bf16_f32 v85, v62, v63
	ds_write_b64 v83, v[84:85]
	v_add_u32_e32 v83, v135, v148
	v_cvt_pk_bf16_f32 v84, v64, v65
	v_cvt_pk_bf16_f32 v85, v66, v67
	ds_write_b64 v83, v[84:85]
	v_add_u32_e32 v83, v135, v149
	v_cvt_pk_bf16_f32 v84, v68, v69
	v_cvt_pk_bf16_f32 v85, v70, v71
	ds_write_b64 v83, v[84:85]
	v_add_u32_e32 v83, v135, v150
	v_cvt_pk_bf16_f32 v84, v72, v73
	v_cvt_pk_bf16_f32 v85, v74, v75
	ds_write_b64 v83, v[84:85]
	v_add_u32_e32 v83, v135, v151
	v_cvt_pk_bf16_f32 v84, v76, v77
	v_cvt_pk_bf16_f32 v85, v78, v79
	ds_write_b64 v83, v[84:85]
	s_and_saveexec_b64 s[86:87], s[8:9]
	s_cbranch_execz .LBB0_289
	s_waitcnt lgkmcnt(6)
	v_add_f32_e32 v80, v80, v81
	v_fmac_f32_e32 v80, v112, v82
	ds_write_b32 v134, v80
	s_branch .LBB0_289

; __device__ __forceinline__ unsigned cvt_pk(float lo, float hi) { unsigned r; asm volatile("v_cvt_pk_bf16_f32 %0, %1, %2" : "=v"(r) : "v"(lo), "v"(hi)); return r; }
; template <int SPLIT> __device__ __forceinline__ void scan_item(const Params& p, unsigned char* smem, const int item, const int vh) {
;     ...
;             __syncthreads();
;             const float m_old = sc[0], M127 = sc[1];
;             const float decay = __expf(m_old - M127);
;             {
;                 const f32x4 a4 = *(const f32x4*)(a_s + sp * 4);
;                 float wsv[4];
; #pragma unroll
;                 for (int i = 0; i < 4; ++i) wsv[i] = __expf(a4[i] - M127);
; #pragma unroll
;                 for (int i = 0; i < 4; ++i) { const u32x4 k = kreg[i]; u32x4 w;
;                     w.x = cvt_pk(bflo(k.x) * wsv[i], bfhi(k.x) * wsv[i]); w.y = cvt_pk(bflo(k.y) * wsv[i], bfhi(k.y) * wsv[i]);
;                     w.z = cvt_pk(bflo(k.z) * wsv[i], bfhi(k.z) * wsv[i]); w.w = cvt_pk(bflo(k.w) * wsv[i], bfhi(k.w) * wsv[i]);
;                     *(u32x4*)(KP + swz(sp * 4 + i, ch)) = w; }
; #pragma unroll
;                 for (int e2 = 0; e2 < 4; ++e2) {
;                     const unsigned k0 = kreg[0][e2], k1 = kreg[1][e2], k2 = kreg[2][e2], k3 = kreg[3][e2];
;                     const unsigned v0 = vreg[0][e2], v1 = vreg[1][e2], v2 = vreg[2][e2], v3 = vreg[3][e2];
;                     const int d0 = ch * 8 + 2 * e2, d1 = d0 + 1; const int co = (sp & 1) * 8;
;                     u32x2 o;
;                     o.x = cvt_pk(bflo(k0) * wsv[0], bflo(k1) * wsv[1]); o.y = cvt_pk(bflo(k2) * wsv[2], bflo(k3) * wsv[3]);
;                     *(u32x2*)(KT + swz(d0, sp >> 1) + co) = o;
;                     o.x = cvt_pk(bfhi(k0) * wsv[0], bfhi(k1) * wsv[1]); o.y = cvt_pk(bfhi(k2) * wsv[2], bfhi(k3) * wsv[3]);
;                     *(u32x2*)(KT + swz(d1, sp >> 1) + co) = o;
;                     o.x = (v0 & 0xffffu) | (v1 << 16); o.y = (v2 & 0xffffu) | (v3 << 16);
;                     *(u32x2*)(VT + swz(d0, sp >> 1) + co) = o;
;                     o.x = (v0 >> 16) | (v1 & 0xffff0000u); o.y = (v2 >> 16) | (v3 & 0xffff0000u);
;                     *(u32x2*)(VT + swz(d1, sp >> 1) + co) = o;
;                 }
;             }
;             const size_t rowl = (size_t)(rfirst + rstep * (j * 128 + wid * 16 + li));
;             __syncthreads();
;             SCAN_LOAD(jn);
.LBB0_316:
	s_or_b64 exec, exec, s[86:87]
	v_mov_b32_e32 v67, s92
	s_waitcnt lgkmcnt(0)
	s_barrier
	ds_read_b64 v[86:87], v67
	ds_read_b128 v[88:91], v98
	s_waitcnt vmcnt(11)
	v_lshlrev_b32_e32 v92, 16, v45
	v_and_b32_e32 v45, 0xffff0000, v45
	v_lshlrev_b32_e32 v94, 16, v46
	v_and_b32_e32 v46, 0xffff0000, v46
	s_waitcnt lgkmcnt(0)
	v_sub_f32_e32 v67, v88, v87
	v_mul_f32_e32 v67, 0x3fb8aa3b, v67
	v_exp_f32_e32 v67, v67
	v_sub_f32_e32 v84, v89, v87
	v_mul_f32_e32 v84, 0x3fb8aa3b, v84
	v_exp_f32_e32 v84, v84
	v_sub_f32_e32 v88, v90, v87
	v_mul_f32_e32 v88, 0x3fb8aa3b, v88
	v_lshlrev_b32_e32 v90, 16, v44
	v_and_b32_e32 v44, 0xffff0000, v44
	v_exp_f32_e32 v88, v88
	v_sub_f32_e32 v89, v91, v87
	v_mul_f32_e32 v90, v67, v90
	v_mul_f32_e32 v91, v67, v44
	v_cvt_pk_bf16_f32 v44, v90, v91
	v_mul_f32_e32 v92, v67, v92
	v_mul_f32_e32 v93, v67, v45
	v_cvt_pk_bf16_f32 v45, v92, v93
	v_mul_f32_e32 v94, v67, v94
	v_mul_f32_e32 v95, v67, v46
	v_cvt_pk_bf16_f32 v46, v94, v95
	v_lshlrev_b32_e32 v151, 16, v47
	v_and_b32_e32 v47, 0xffff0000, v47
	v_mul_f32_e32 v89, 0x3fb8aa3b, v89
	v_mul_f32_e32 v151, v67, v151
	v_mul_f32_e32 v67, v67, v47
	v_cvt_pk_bf16_f32 v47, v151, v67
	ds_write_b128 v133, v[44:47]
	s_waitcnt vmcnt(10)
	v_lshlrev_b32_e32 v44, 16, v40
	v_and_b32_e32 v40, 0xffff0000, v40
	v_lshlrev_b32_e32 v46, 16, v41
	v_and_b32_e32 v41, 0xffff0000, v41
	v_lshlrev_b32_e32 v152, 16, v42
	v_and_b32_e32 v42, 0xffff0000, v42
	v_exp_f32_e32 v89, v89
	v_mul_f32_e32 v44, v84, v44
	v_mul_f32_e32 v45, v84, v40
	v_cvt_pk_bf16_f32 v40, v44, v45
	v_mul_f32_e32 v46, v84, v46
	v_mul_f32_e32 v47, v84, v41
	v_cvt_pk_bf16_f32 v41, v46, v47
	v_mul_f32_e32 v152, v84, v152
	v_mul_f32_e32 v153, v84, v42
	v_cvt_pk_bf16_f32 v42, v152, v153
	v_lshlrev_b32_e32 v154, 16, v43
	v_and_b32_e32 v43, 0xffff0000, v43
	v_mul_f32_e32 v154, v84, v154
	v_mul_f32_e32 v84, v84, v43
	v_cvt_pk_bf16_f32 v43, v154, v84
	ds_write_b128 v134, v[40:43]
	s_waitcnt vmcnt(9)
	v_lshlrev_b32_e32 v40, 16, v36
	v_and_b32_e32 v36, 0xffff0000, v36
	v_lshlrev_b32_e32 v42, 16, v37
	v_and_b32_e32 v37, 0xffff0000, v37
	v_lshlrev_b32_e32 v155, 16, v38
	v_and_b32_e32 v38, 0xffff0000, v38
	v_mul_f32_e32 v40, v88, v40
	v_mul_f32_e32 v41, v88, v36
	v_cvt_pk_bf16_f32 v36, v40, v41
	v_mul_f32_e32 v42, v88, v42
	v_mul_f32_e32 v43, v88, v37
	v_cvt_pk_bf16_f32 v37, v42, v43
	v_mul_f32_e32 v155, v88, v155
	v_mul_f32_e32 v156, v88, v38
	v_cvt_pk_bf16_f32 v38, v155, v156
	v_lshlrev_b32_e32 v157, 16, v39
	v_and_b32_e32 v39, 0xffff0000, v39
	v_mul_f32_e32 v157, v88, v157
	v_mul_f32_e32 v88, v88, v39
	v_cvt_pk_bf16_f32 v39, v157, v88
	ds_write_b128 v135, v[36:39]
	s_waitcnt vmcnt(7)
	v_lshlrev_b32_e32 v36, 16, v32
	v_and_b32_e32 v32, 0xffff0000, v32
	v_lshlrev_b32_e32 v38, 16, v33
	v_and_b32_e32 v33, 0xffff0000, v33
	v_lshlrev_b32_e32 v158, 16, v34
	v_and_b32_e32 v34, 0xffff0000, v34
	v_mul_f32_e32 v36, v89, v36
	v_mul_f32_e32 v37, v89, v32
	v_cvt_pk_bf16_f32 v32, v36, v37
	v_mul_f32_e32 v38, v89, v38
	v_mul_f32_e32 v39, v89, v33
	v_cvt_pk_bf16_f32 v33, v38, v39
	v_mul_f32_e32 v158, v89, v158
	v_mul_f32_e32 v159, v89, v34
	v_cvt_pk_bf16_f32 v34, v158, v159
	v_lshlrev_b32_e32 v160, 16, v35
	v_and_b32_e32 v35, 0xffff0000, v35
	v_mul_f32_e32 v160, v89, v160
	v_mul_f32_e32 v89, v89, v35
	v_cvt_pk_bf16_f32 v35, v160, v89
	ds_write_b128 v136, v[32:35]
	v_cvt_pk_bf16_f32 v32, v90, v44
	v_cvt_pk_bf16_f32 v33, v40, v36
	v_add_u32_e32 v34, v102, v123
	ds_write_b64 v34, v[32:33]
	v_cvt_pk_bf16_f32 v32, v91, v45
	v_cvt_pk_bf16_f32 v33, v41, v37
	v_add_u32_e32 v34, v102, v124
	ds_write_b64 v34, v[32:33]
	s_waitcnt vmcnt(4)
	v_lshlrev_b32_e32 v32, 16, v4
	v_lshlrev_b32_e32 v33, 16, v16
	v_and_or_b32 v32, v0, s95, v32
	v_and_or_b32 v33, v8, s95, v33
	v_add_u32_e32 v34, v103, v123
	v_lshrrev_b32_e32 v0, 16, v0
	ds_write_b64 v34, v[32:33] offset:32768
	v_and_or_b32 v32, v4, s94, v0
	v_lshrrev_b32_e32 v0, 16, v8
	v_and_or_b32 v33, v16, s94, v0
	v_add_u32_e32 v0, v103, v124
	ds_write_b64 v0, v[32:33] offset:32768
	v_add_u32_e32 v0, v102, v125
	v_cvt_pk_bf16_f32 v32, v92, v46
	v_cvt_pk_bf16_f32 v33, v42, v38
	ds_write_b64 v0, v[32:33]
	v_add_u32_e32 v0, v102, v126
	v_cvt_pk_bf16_f32 v32, v93, v47
	v_cvt_pk_bf16_f32 v33, v43, v39
	ds_write_b64 v0, v[32:33]
	v_lshlrev_b32_e32 v0, 16, v5
	v_and_or_b32 v32, v1, s95, v0
	v_lshlrev_b32_e32 v0, 16, v17
	v_and_or_b32 v33, v9, s95, v0
	v_add_u32_e32 v0, v103, v125
	ds_write_b64 v0, v[32:33] offset:32768
	v_lshrrev_b32_e32 v0, 16, v1
	v_lshrrev_b32_e32 v1, 16, v9
	v_and_or_b32 v0, v5, s94, v0
	v_and_or_b32 v1, v17, s94, v1
	v_add_u32_e32 v4, v103, v126
	ds_write_b64 v4, v[0:1] offset:32768
	v_cvt_pk_bf16_f32 v0, v94, v152
	v_cvt_pk_bf16_f32 v1, v155, v158
	v_add_u32_e32 v4, v102, v127
	ds_write_b64 v4, v[0:1]
	v_cvt_pk_bf16_f32 v0, v95, v153
	v_cvt_pk_bf16_f32 v1, v156, v159
	v_add_u32_e32 v4, v102, v128
	ds_write_b64 v4, v[0:1]
	v_lshlrev_b32_e32 v0, 16, v6
	v_lshlrev_b32_e32 v1, 16, v18
	v_and_or_b32 v0, v2, s95, v0
	v_and_or_b32 v1, v10, s95, v1
	v_add_u32_e32 v4, v103, v127
	ds_write_b64 v4, v[0:1] offset:32768
	v_lshrrev_b32_e32 v0, 16, v2
	v_lshrrev_b32_e32 v1, 16, v10
	v_and_or_b32 v0, v6, s94, v0
	v_and_or_b32 v1, v18, s94, v1
	v_add_u32_e32 v2, v103, v128
	ds_write_b64 v2, v[0:1] offset:32768
	v_cvt_pk_bf16_f32 v0, v151, v154
	v_cvt_pk_bf16_f32 v1, v157, v160
	v_add_u32_e32 v2, v102, v129
	ds_write_b64 v2, v[0:1]
	v_cvt_pk_bf16_f32 v0, v67, v84
	v_cvt_pk_bf16_f32 v1, v88, v89
	v_add_u32_e32 v2, v102, v130
	ds_write_b64 v2, v[0:1]
	v_lshlrev_b32_e32 v0, 16, v7
	v_lshlrev_b32_e32 v1, 16, v19
	v_and_or_b32 v0, v3, s95, v0
	v_and_or_b32 v1, v11, s95, v1
	v_add_u32_e32 v2, v103, v129
	ds_write_b64 v2, v[0:1] offset:32768
	v_lshrrev_b32_e32 v0, 16, v3
	v_lshrrev_b32_e32 v1, 16, v11
	v_and_or_b32 v0, v7, s94, v0
	v_and_or_b32 v1, v19, s94, v1
	v_add_u32_e32 v2, v103, v130
	s_lshl_b32 s0, vcc_lo, 7
	ds_write_b64 v2, v[0:1] offset:32768
	v_or_b32_e32 v0, s0, v85
	v_mul_lo_u32 v0, v0, s3
	v_add_u32_e32 v4, s33, v0
	v_ashrrev_i32_e32 v5, 31, v4
	v_lshlrev_b64 v[0:1], 10, v[4:5]
	v_add_u32_e32 v8, s3, v4
	v_lshl_add_u64 v[0:1], v[64:65], 0, v[0:1]
	v_ashrrev_i32_e32 v9, 31, v8
	s_waitcnt lgkmcnt(0)
	s_barrier
; #define SCAN_LOAD(j) do { \
;         _Pragma("unroll") for (int i = 0; i < 4; ++i) { const size_t r = (size_t)(rfirst + rstep * ((j) * 128 + sp * 4 + i)); \
;             kreg[i] = *(const u32x4*)(K0 + r * 512 + h * 128 + ch * 8); vreg[i] = *(const u32x4*)(P0 + r * LDP + 1536 + h * 128 + ch * 8); } \
;         } while (0)
; template <int SPLIT> __device__ __forceinline__ void scan_item(const Params& p, unsigned char* smem, const int item, const int vh) {
;     ...
;             SCAN_LOAD(jn);
;             __builtin_amdgcn_sched_barrier(0);
;             const int l = wid * 16 + li;
;             const float Ml = M_s[l], gl = g_s[l];
;             f32x4 acc[8];
; #pragma unroll
;             for (int nb = 0; nb < 8; ++nb) acc[nb] = (f32x4){0.f, 0.f, 0.f, 0.f};
;             mm16<8>(acc, KP, qf, lane);
	global_load_dwordx4 v[44:47], v[0:1], off
	v_mad_i64_i32 v[0:1], s[4:5], v4, s88, v[80:81]
	v_lshlrev_b64 v[4:5], 10, v[8:9]
	v_add_u32_e32 v16, s3, v8
	v_lshl_add_u64 v[4:5], v[64:65], 0, v[4:5]
	v_ashrrev_i32_e32 v17, 31, v16
	global_load_dwordx4 v[40:43], v[4:5], off
	v_mad_i64_i32 v[4:5], s[4:5], v8, s88, v[80:81]
	v_lshlrev_b64 v[8:9], 10, v[16:17]
	v_lshl_add_u64 v[8:9], v[64:65], 0, v[8:9]
	global_load_dwordx4 v[36:39], v[8:9], off
	v_mad_i64_i32 v[8:9], s[4:5], v16, s88, v[80:81]
	v_add_u32_e32 v16, s3, v16
	v_ashrrev_i32_e32 v17, 31, v16
	v_lshlrev_b64 v[18:19], 10, v[16:17]
	v_lshl_add_u64 v[18:19], v[64:65], 0, v[18:19]
	v_mad_i64_i32 v[16:17], s[4:5], v16, s88, v[80:81]
	global_load_dwordx4 v[0:3], v[0:1], off offset:3072
	v_sub_f32_e32 v67, v86, v87
	global_load_dwordx4 v[4:7], v[4:5], off offset:3072
	v_mul_f32_e32 v67, 0x3fb8aa3b, v67
	global_load_dwordx4 v[8:11], v[8:9], off offset:3072
	v_exp_f32_e32 v84, v67
	global_load_dwordx4 v[32:35], v[18:19], off
	s_nop 0
	global_load_dwordx4 v[16:19], v[16:17], off offset:3072
	v_add_u32_e32 v67, 0, v107
	ds_read_b128 v[88:91], v67
	ds_read_b128 v[92:95], v67 offset:4096
	ds_read_b32 v151, v105
	ds_read_b128 v[152:155], v67 offset:8192
	ds_read_b128 v[156:159], v67 offset:12288
	ds_read_b32 v171, v104
	s_waitcnt vmcnt(11) lgkmcnt(5)
	v_mfma_f32_16x16x32_bf16 v[88:91], v[88:91], v[28:31], 0
	s_waitcnt lgkmcnt(4)
	v_mfma_f32_16x16x32_bf16 v[92:95], v[92:95], v[28:31], 0
	s_waitcnt lgkmcnt(2)
	v_mfma_f32_16x16x32_bf16 v[152:155], v[152:155], v[28:31], 0
	s_waitcnt lgkmcnt(1)
	v_mfma_f32_16x16x32_bf16 v[156:159], v[156:159], v[28:31], 0
	ds_read_b128 v[160:163], v67 offset:16384
	ds_read_b128 v[164:167], v67 offset:20480
	ds_read_b128 v[172:175], v67 offset:24576
	ds_read_b128 v[178:181], v67 offset:28672
	s_waitcnt lgkmcnt(3)
	v_mfma_f32_16x16x32_bf16 v[160:163], v[160:163], v[28:31], 0
	s_waitcnt lgkmcnt(2)
	v_mfma_f32_16x16x32_bf16 v[164:167], v[164:167], v[28:31], 0
	s_waitcnt lgkmcnt(1)
	v_mfma_f32_16x16x32_bf16 v[172:175], v[172:175], v[28:31], 0
	s_waitcnt lgkmcnt(0)
	v_mfma_f32_16x16x32_bf16 v[178:181], v[178:181], v[28:31], 0
	v_add_u32_e32 v246, 0, v109
	ds_read_b128 v[218:221], v246
	ds_read_b128 v[222:225], v246 offset:4096
	ds_read_b128 v[226:229], v246 offset:8192
	ds_read_b128 v[230:233], v246 offset:12288
	ds_read_b128 v[234:237], v246 offset:16384
	v_add_u32_e32 v67, 0, v109
	ds_read_b128 v[238:241], v246 offset:20480
	s_waitcnt vmcnt(10) lgkmcnt(5)
	v_mfma_f32_16x16x32_bf16 v[88:91], v[218:221], v[24:27], v[88:91]
	ds_read_b128 v[218:221], v246 offset:24576
	s_waitcnt lgkmcnt(5)
	v_mfma_f32_16x16x32_bf16 v[92:95], v[222:225], v[24:27], v[92:95]
	ds_read_b128 v[222:225], v246 offset:28672
	s_waitcnt lgkmcnt(5)
	v_mfma_f32_16x16x32_bf16 v[152:155], v[226:229], v[24:27], v[152:155]
	v_add_u32_e32 v247, 0, v111
	ds_read_b128 v[226:229], v247
	s_waitcnt lgkmcnt(5)
	v_mfma_f32_16x16x32_bf16 v[156:159], v[230:233], v[24:27], v[156:159]
	ds_read_b128 v[230:233], v247 offset:4096
	s_waitcnt lgkmcnt(5)
	v_mfma_f32_16x16x32_bf16 v[160:163], v[234:237], v[24:27], v[160:163]
	ds_read_b128 v[234:237], v247 offset:8192
	s_waitcnt lgkmcnt(5)
	v_mfma_f32_16x16x32_bf16 v[164:167], v[238:241], v[24:27], v[164:167]
	ds_read_b128 v[238:241], v247 offset:12288
	s_waitcnt lgkmcnt(5)
	v_mfma_f32_16x16x32_bf16 v[172:175], v[218:221], v[24:27], v[172:175]
	ds_read_b128 v[218:221], v247 offset:16384
	s_waitcnt lgkmcnt(5)
	v_mfma_f32_16x16x32_bf16 v[178:181], v[222:225], v[24:27], v[178:181]
	v_add_u32_e32 v67, 0, v111
	ds_read_b128 v[222:225], v247 offset:20480
	s_waitcnt vmcnt(9) lgkmcnt(5)
	v_mfma_f32_16x16x32_bf16 v[88:91], v[226:229], v[20:23], v[88:91]
	ds_read_b128 v[226:229], v247 offset:24576
	s_waitcnt lgkmcnt(5)
	v_mfma_f32_16x16x32_bf16 v[92:95], v[230:233], v[20:23], v[92:95]
	ds_read_b128 v[230:233], v247 offset:28672
	s_waitcnt lgkmcnt(5)
	v_mfma_f32_16x16x32_bf16 v[152:155], v[234:237], v[20:23], v[152:155]
	v_add_u32_e32 v248, 0, v113
	ds_read_b128 v[234:237], v248
	s_waitcnt lgkmcnt(5)
	v_mfma_f32_16x16x32_bf16 v[156:159], v[238:241], v[20:23], v[156:159]
	ds_read_b128 v[238:241], v248 offset:4096
	s_waitcnt lgkmcnt(5)
	v_mfma_f32_16x16x32_bf16 v[160:163], v[218:221], v[20:23], v[160:163]
	ds_read_b128 v[218:221], v248 offset:8192
	s_waitcnt lgkmcnt(5)
	v_mfma_f32_16x16x32_bf16 v[164:167], v[222:225], v[20:23], v[164:167]
	ds_read_b128 v[222:225], v248 offset:12288
	s_waitcnt lgkmcnt(5)
	v_mfma_f32_16x16x32_bf16 v[172:175], v[226:229], v[20:23], v[172:175]
	ds_read_b128 v[226:229], v248 offset:16384
	s_waitcnt lgkmcnt(5)
	v_mfma_f32_16x16x32_bf16 v[178:181], v[230:233], v[20:23], v[178:181]
	v_add_u32_e32 v67, 0, v113
	ds_read_b128 v[230:233], v248 offset:20480
	s_waitcnt vmcnt(8) lgkmcnt(5)
	v_mfma_f32_16x16x32_bf16 v[88:91], v[234:237], v[12:15], v[88:91]
	ds_read_b128 v[234:237], v248 offset:24576
	s_waitcnt lgkmcnt(5)
	v_mfma_f32_16x16x32_bf16 v[92:95], v[238:241], v[12:15], v[92:95]
	ds_read_b128 v[238:241], v248 offset:28672
	s_waitcnt lgkmcnt(5)
	v_mfma_f32_16x16x32_bf16 v[152:155], v[218:221], v[12:15], v[152:155]
	s_nop 0
	s_waitcnt lgkmcnt(4)
	v_mfma_f32_16x16x32_bf16 v[156:159], v[222:225], v[12:15], v[156:159]
	s_nop 0
	s_waitcnt lgkmcnt(3)
	v_mfma_f32_16x16x32_bf16 v[160:163], v[226:229], v[12:15], v[160:163]
	s_nop 0
	s_waitcnt lgkmcnt(2)
	v_mfma_f32_16x16x32_bf16 v[164:167], v[230:233], v[12:15], v[164:167]
	s_nop 0
	s_waitcnt lgkmcnt(1)
	v_mfma_f32_16x16x32_bf16 v[172:175], v[234:237], v[12:15], v[172:175]
	s_nop 0
	s_waitcnt lgkmcnt(0)
	v_mfma_f32_16x16x32_bf16 v[178:181], v[238:241], v[12:15], v[178:181]
	v_mov_b32_e32 v67, s6
	ds_read_b32 v67, v67
	s_waitcnt lgkmcnt(0)
; __device__ __forceinline__ unsigned cvt_pk(float lo, float hi) { unsigned r; asm volatile("v_cvt_pk_bf16_f32 %0, %1, %2" : "=v"(r) : "v"(lo), "v"(hi)); return r; }
; __device__ __forceinline__ float bflo(unsigned w) { return __uint_as_float(w << 16); }
; __device__ __forceinline__ float bfhi(unsigned w) { return __uint_as_float(w & 0xffff0000u); }
; template <int SPLIT> __device__ __forceinline__ void scan_item(const Params& p, unsigned char* smem, const int item, const int vh) {
;     ...
;             float rs = 0.f; u32x2 pp[8];
;             const float rowf = __expf(fminf(sc[1] - Ml, 80.f));
; #pragma unroll
;             for (int nb = 0; nb < 8; ++nb) { float pv[4];
; #pragma unroll
;                 for (int jj = 0; jj < 4; ++jj) { const int s = nb * 16 + kq * 4 + jj; pv[jj] = (s <= l) ? acc[nb][jj] * rowf : 0.f; rs += pv[jj]; }
;                 pp[nb].x = cvt_pk(pv[0], pv[1]); pp[nb].y = cvt_pk(pv[2], pv[3]); }
;             __builtin_amdgcn_sched_barrier(0);
;             float nq = 0.f;
; #pragma unroll
;             for (int ks = 0; ks < 4; ++ks) { const f32x4 n0 = *(const f32x4*)(n_s + ks * 32 + kq * 8), n1 = *(const f32x4*)(n_s + ks * 32 + kq * 8 + 4);
;                 const u32x4 qw = *(const u32x4*)&qf[ks];
;                 nq += bflo(qw.x) * n0[0] + bfhi(qw.x) * n0[1] + bflo(qw.y) * n0[2] + bfhi(qw.y) * n0[3] + bflo(qw.z) * n1[0] + bfhi(qw.z) * n1[1] + bflo(qw.w) * n1[2] + bfhi(qw.w) * n1[3]; }
	v_sub_f32_e32 v67, v67, v171
	v_min_f32_e32 v67, 0x42a00000, v67
	v_mul_f32_e32 v67, 0x3fb8aa3b, v67
	v_exp_f32_e32 v87, v67
	s_nop 0
	v_mul_f32_e32 v67, v88, v87
	v_mul_f32_e32 v88, v89, v87
	v_cndmask_b32_e64 v67, v67, 0, s[10:11]
	v_mul_f32_e32 v89, v90, v87
	v_mul_f32_e32 v90, v91, v87
	v_cndmask_b32_e64 v91, 0, v88, s[12:13]
	v_add_f32_e32 v168, 0, v67
	v_cndmask_b32_e64 v89, v89, 0, s[14:15]
	v_cvt_pk_bf16_f32 v88, v67, v91
	v_add_f32_e32 v67, v91, v168
	v_cndmask_b32_e64 v90, v90, 0, s[16:17]
	v_add_f32_e32 v67, v89, v67
	v_add_f32_e32 v67, v90, v67
	v_cvt_pk_bf16_f32 v89, v89, v90
	v_mul_f32_e32 v90, v92, v87
	v_cndmask_b32_e64 v90, v90, 0, s[18:19]
	v_mul_f32_e32 v91, v93, v87
	v_add_f32_e32 v67, v90, v67
	v_cndmask_b32_e64 v91, v91, 0, s[20:21]
	v_mul_f32_e32 v92, v94, v87
	v_add_f32_e32 v67, v91, v67
	v_cndmask_b32_e64 v92, v92, 0, s[22:23]
	v_mul_f32_e32 v93, v95, v87
	v_add_f32_e32 v67, v92, v67
	v_cndmask_b32_e64 v93, v93, 0, s[24:25]
	v_cvt_pk_bf16_f32 v90, v90, v91
	v_cvt_pk_bf16_f32 v91, v92, v93
	v_mul_f32_e32 v92, v152, v87
	v_add_f32_e32 v67, v93, v67
	v_cndmask_b32_e64 v92, v92, 0, s[26:27]
	v_mul_f32_e32 v93, v153, v87
	v_add_f32_e32 v67, v92, v67
	v_cndmask_b32_e64 v93, v93, 0, s[28:29]
	v_mul_f32_e32 v94, v154, v87
	v_add_f32_e32 v67, v93, v67
	v_cndmask_b32_e64 v94, v94, 0, s[30:31]
	v_mul_f32_e32 v95, v155, v87
	v_add_f32_e32 v67, v94, v67
	v_cndmask_b32_e64 v95, v95, 0, s[34:35]
	v_cvt_pk_bf16_f32 v92, v92, v93
	v_cvt_pk_bf16_f32 v93, v94, v95
	v_mul_f32_e32 v94, v156, v87
	v_add_f32_e32 v67, v95, v67
	v_cndmask_b32_e64 v94, v94, 0, s[36:37]
	v_mul_f32_e32 v95, v157, v87
	v_add_f32_e32 v67, v94, v67
	v_cndmask_b32_e64 v95, v95, 0, s[38:39]
	v_mul_f32_e32 v152, v158, v87
	v_add_f32_e32 v67, v95, v67
	v_cndmask_b32_e64 v152, v152, 0, s[40:41]
	v_mul_f32_e32 v153, v159, v87
	v_add_f32_e32 v67, v152, v67
	v_cndmask_b32_e64 v153, v153, 0, s[42:43]
	v_cvt_pk_bf16_f32 v94, v94, v95
	v_cvt_pk_bf16_f32 v95, v152, v153
	v_mul_f32_e32 v152, v160, v87
	v_add_f32_e32 v67, v153, v67
	v_cndmask_b32_e64 v152, v152, 0, s[44:45]
	v_mul_f32_e32 v153, v161, v87
	v_add_f32_e32 v67, v152, v67
	v_cndmask_b32_e64 v153, v153, 0, s[46:47]
	v_mul_f32_e32 v154, v162, v87
	v_add_f32_e32 v67, v153, v67
	v_cndmask_b32_e64 v154, v154, 0, s[48:49]
	v_mul_f32_e32 v155, v163, v87
	v_add_f32_e32 v67, v154, v67
	v_cndmask_b32_e64 v155, v155, 0, s[50:51]
	v_cvt_pk_bf16_f32 v168, v152, v153
	v_mul_f32_e32 v152, v164, v87
	v_add_f32_e32 v67, v155, v67
	v_cndmask_b32_e64 v152, v152, 0, s[52:53]
	v_add_f32_e32 v161, v152, v67
	v_mul_f32_e32 v67, v165, v87
	v_cndmask_b32_e64 v163, v67, 0, s[54:55]
	v_mul_f32_e32 v67, v166, v87
	v_cndmask_b32_e64 v183, v67, 0, s[56:57]
	v_mul_f32_e32 v67, v167, v87
	v_cndmask_b32_e64 v185, v67, 0, s[58:59]
	v_mul_f32_e32 v67, v172, v87
	v_cndmask_b32_e64 v189, v67, 0, s[60:61]
	v_mul_f32_e32 v67, v173, v87
	v_cndmask_b32_e64 v173, v67, 0, s[62:63]
	v_mul_f32_e32 v67, v174, v87
	v_cndmask_b32_e64 v191, v67, 0, s[64:65]
	v_mul_f32_e32 v67, v175, v87
	v_cvt_pk_bf16_f32 v169, v154, v155
	v_cvt_pk_bf16_f32 v186, v152, v163
	v_cndmask_b32_e64 v175, v67, 0, s[66:67]
	v_mul_f32_e32 v67, v178, v87
	v_mul_f32_e32 v152, v179, v87
	v_cndmask_b32_e64 v67, v67, 0, s[68:69]
	v_cndmask_b32_e64 v177, v152, 0, s[70:71]
	v_mul_f32_e32 v152, v180, v87
	v_mul_f32_e32 v87, v181, v87
	v_cvt_pk_bf16_f32 v187, v183, v185
	v_cvt_pk_bf16_f32 v192, v189, v173
	v_cvt_pk_bf16_f32 v193, v191, v175
	v_cndmask_b32_e64 v200, v152, 0, s[72:73]
	v_cndmask_b32_e64 v201, v87, 0, s[74:75]
	v_cvt_pk_bf16_f32 v178, v67, v177
	v_cvt_pk_bf16_f32 v179, v200, v201
	ds_read_b128 v[152:155], v137
	ds_read_b128 v[156:159], v137 offset:16
	v_lshlrev_b32_e32 v87, 16, v28
	v_and_b32_e32 v160, 0xffff0000, v28
	v_and_b32_e32 v195, 0xffff0000, v27
	s_waitcnt lgkmcnt(1)
	v_mul_f32_e32 v162, v152, v87
	v_lshlrev_b32_e32 v87, 16, v29
	v_mul_f32_e32 v182, v154, v87
	v_and_b32_e32 v87, 0xffff0000, v29
	v_mul_f32_e32 v160, v153, v160
	v_mul_f32_e32 v184, v155, v87
	v_lshlrev_b32_e32 v87, 16, v30
	ds_read_b128 v[152:155], v137 offset:128
	s_waitcnt lgkmcnt(1)
	v_mul_f32_e32 v188, v156, v87
	v_and_b32_e32 v87, 0xffff0000, v30
	v_mul_f32_e32 v172, v157, v87
	v_lshlrev_b32_e32 v87, 16, v31
	v_mul_f32_e32 v190, v158, v87
	v_and_b32_e32 v87, 0xffff0000, v31
	v_pk_add_f32 v[180:181], v[162:163], v[160:161]
	v_mul_f32_e32 v174, v159, v87
	ds_read_b128 v[156:159], v137 offset:144
	v_and_b32_e32 v161, 0xffff0000, v24
	v_lshlrev_b32_e32 v160, 16, v24
	s_waitcnt lgkmcnt(1)
	v_mul_f32_e32 v162, v153, v161
	v_pk_fma_f32 v[152:153], v[152:153], v[160:161], v[162:163] op_sel_hi:[1,1,0]
	v_and_b32_e32 v161, 0xffff0000, v25
	v_lshlrev_b32_e32 v160, 16, v25
	v_pk_fma_f32 v[152:153], v[154:155], v[160:161], v[152:153]
	v_mul_f32_e32 v154, v155, v161
	v_pk_add_f32 v[152:153], v[154:155], v[152:153] op_sel_hi:[0,1]
	v_and_b32_e32 v155, 0xffff0000, v26
	v_lshlrev_b32_e32 v154, 16, v26
	s_waitcnt lgkmcnt(0)
	v_pk_fma_f32 v[152:153], v[156:157], v[154:155], v[152:153]
	v_mul_f32_e32 v154, v157, v155
	v_pk_add_f32 v[156:157], v[154:155], v[152:153] op_sel_hi:[0,1]
	ds_read_b128 v[152:155], v137 offset:256
	ds_read_b128 v[160:163], v137 offset:272
	v_lshlrev_b32_e32 v194, 16, v27
	v_and_b32_e32 v165, 0xffff0000, v20
	v_pk_fma_f32 v[156:157], v[158:159], v[194:195], v[156:157]
	v_lshlrev_b32_e32 v164, 16, v20
	s_waitcnt lgkmcnt(1)
	v_mul_f32_e32 v158, v153, v165
	v_pk_fma_f32 v[152:153], v[152:153], v[164:165], v[158:159] op_sel_hi:[1,1,0]
	v_and_b32_e32 v165, 0xffff0000, v21
	v_lshlrev_b32_e32 v164, 16, v21
	v_pk_fma_f32 v[152:153], v[154:155], v[164:165], v[152:153]
	v_mul_f32_e32 v154, v155, v165
	v_pk_add_f32 v[152:153], v[154:155], v[152:153] op_sel_hi:[0,1]
	v_and_b32_e32 v155, 0xffff0000, v22
	v_lshlrev_b32_e32 v154, 16, v22
	s_waitcnt lgkmcnt(0)
; template <int SPLIT> __device__ __forceinline__ void scan_item(const Params& p, unsigned char* smem, const int item, const int vh) {
;     ...
;             rs += __shfl_xor(rs, 16); rs += __shfl_xor(rs, 32); nq += __shfl_xor(nq, 16); nq += __shfl_xor(nq, 32);
;             const float exl = __expf(m_old - Ml);
;             const float den = rs + exl * nq;
;             const float hinv = __builtin_amdgcn_rcpf(fmaxf(fabsf(den), __expf(-(gl + Ml))));
;             __syncthreads();
; #pragma unroll
;             for (int nb = 0; nb < 8; ++nb) *(u32x2*)(KP + swz(l, nb * 2 + (kq >> 1)) + (kq & 1) * 8) = pp[nb];
;             f32x4 acc2[NBV];
; #pragma unroll
;             for (int nb = 0; nb < NBV; ++nb) acc2[nb] = (f32x4){0.f, 0.f, 0.f, 0.f};
;             __builtin_amdgcn_sched_barrier(0);
;             mm16<NBV>(acc2, CS + vh * 16384, qf, lane);
;             __builtin_amdgcn_sched_barrier(0);
	v_pk_fma_f32 v[152:153], v[160:161], v[154:155], v[152:153]
	v_mul_f32_e32 v154, v161, v155
	v_pk_add_f32 v[160:161], v[154:155], v[152:153] op_sel_hi:[0,1]
	ds_read_b128 v[152:155], v137 offset:384
	ds_read_b128 v[164:167], v137 offset:400
	v_and_b32_e32 v199, 0xffff0000, v12
	v_lshlrev_b32_e32 v198, 16, v12
	v_and_b32_e32 v197, 0xffff0000, v23
	s_waitcnt lgkmcnt(1)
	v_mul_f32_e32 v158, v153, v199
	v_pk_fma_f32 v[152:153], v[152:153], v[198:199], v[158:159] op_sel_hi:[1,1,0]
	v_and_b32_e32 v199, 0xffff0000, v13
	v_lshlrev_b32_e32 v198, 16, v13
	v_pk_fma_f32 v[152:153], v[154:155], v[198:199], v[152:153]
	v_mul_f32_e32 v154, v155, v199
	v_pk_add_f32 v[152:153], v[154:155], v[152:153] op_sel_hi:[0,1]
	v_and_b32_e32 v155, 0xffff0000, v14
	v_lshlrev_b32_e32 v154, 16, v14
	s_waitcnt lgkmcnt(0)
	v_pk_fma_f32 v[152:153], v[164:165], v[154:155], v[152:153]
	v_mul_f32_e32 v154, v165, v155
	v_pk_add_f32 v[164:165], v[182:183], v[180:181]
	v_pk_add_f32 v[152:153], v[154:155], v[152:153] op_sel_hi:[0,1]
	v_pk_add_f32 v[164:165], v[184:185], v[164:165]
	v_and_b32_e32 v155, 0xffff0000, v15
	v_lshlrev_b32_e32 v154, 16, v15
	v_pk_add_f32 v[164:165], v[188:189], v[164:165]
	v_lshlrev_b32_e32 v196, 16, v23
	v_pk_fma_f32 v[152:153], v[166:167], v[154:155], v[152:153]
	v_and_b32_e32 v154, 64, v150
	v_pk_add_f32 v[164:165], v[172:173], v[164:165]
	v_pk_fma_f32 v[160:161], v[162:163], v[196:197], v[160:161]
	v_add_u32_e32 v162, 64, v154
	v_pk_add_f32 v[164:165], v[190:191], v[164:165]
	v_mul_f32_e32 v154, v159, v195
	v_pk_add_f32 v[164:165], v[174:175], v[164:165]
	v_pk_add_f32 v[156:157], v[154:155], v[156:157] op_sel_hi:[0,1]
	v_mul_f32_e32 v154, v163, v197
	v_xor_b32_e32 v87, 16, v150
	v_pk_add_f32 v[164:165], v[66:67], v[164:165]
	v_mov_b32_e32 v157, v177
	v_pk_add_f32 v[158:159], v[154:155], v[160:161] op_sel_hi:[0,1]
	v_mul_f32_e32 v154, v167, v155
	v_cmp_lt_i32_e32 vcc, v87, v162
	v_pk_add_f32 v[156:157], v[156:157], v[164:165]
	v_mov_b32_e32 v159, v200
	v_pk_add_f32 v[152:153], v[154:155], v[152:153] op_sel_hi:[0,1]
	v_cndmask_b32_e32 v87, v150, v87, vcc
	v_pk_add_f32 v[156:157], v[158:159], v[156:157]
	v_mov_b32_e32 v153, v201
	v_lshlrev_b32_e32 v87, 2, v87
	v_pk_add_f32 v[152:153], v[152:153], v[156:157]
	ds_bpermute_b32 v155, v87, v153
	ds_bpermute_b32 v154, v87, v152
	v_xor_b32_e32 v67, 32, v150
	v_cmp_lt_i32_e32 vcc, v67, v162
	v_sub_f32_e32 v86, v86, v171
	v_mul_f32_e32 v86, 0x3fb8aa3b, v86
	v_cndmask_b32_e32 v67, v150, v67, vcc
	v_lshlrev_b32_e32 v67, 2, v67
	s_waitcnt lgkmcnt(0)
	v_pk_add_f32 v[152:153], v[152:153], v[154:155]
	ds_bpermute_b32 v155, v67, v153
	ds_bpermute_b32 v154, v67, v152
	v_add_f32_e32 v151, v171, v151
	v_exp_f32_e32 v86, v86
	v_mul_f32_e32 v151, 0xbfb8aa3b, v151
	v_exp_f32_e32 v151, v151
	s_waitcnt lgkmcnt(0)
	v_pk_add_f32 v[152:153], v[152:153], v[154:155]
	s_nop 0
	v_fmac_f32_e32 v153, v86, v152
	v_max_f32_e64 v151, |v153|, v151
	s_barrier
	ds_write_b64 v138, v[88:89]
	ds_write_b64 v139, v[90:91]
	ds_write_b64 v140, v[92:93]
	ds_write_b64 v141, v[94:95]
	ds_write_b64 v142, v[168:169]
	ds_write_b64 v143, v[186:187]
	ds_write_b64 v144, v[192:193]
	ds_write_b64 v145, v[178:179]
	v_add_u32_e32 v156, s89, v107
	ds_read_b128 v[88:91], v156
	ds_read_b128 v[92:95], v156 offset:4096
	ds_read_b128 v[152:155], v156 offset:8192
	ds_read_b128 v[156:159], v156 offset:12288
	s_waitcnt lgkmcnt(3)
	v_mfma_f32_16x16x32_bf16 v[88:91], v[88:91], v[28:31], 0
	s_waitcnt lgkmcnt(2)
	v_mfma_f32_16x16x32_bf16 v[92:95], v[92:95], v[28:31], 0
	s_waitcnt lgkmcnt(1)
	v_mfma_f32_16x16x32_bf16 v[152:155], v[152:155], v[28:31], 0
	s_waitcnt lgkmcnt(0)
	v_mfma_f32_16x16x32_bf16 v[28:31], v[156:159], v[28:31], 0
	v_add_u32_e32 v249, s89, v109
	ds_read_b128 v[218:221], v249
	ds_read_b128 v[222:225], v249 offset:4096
	ds_read_b128 v[226:229], v249 offset:8192
	ds_read_b128 v[230:233], v249 offset:12288
	v_add_u32_e32 v160, s89, v109
	s_nop 0
	s_waitcnt lgkmcnt(3)
	v_mfma_f32_16x16x32_bf16 v[88:91], v[218:221], v[24:27], v[88:91]
	s_nop 0
	s_waitcnt lgkmcnt(2)
	v_mfma_f32_16x16x32_bf16 v[92:95], v[222:225], v[24:27], v[92:95]
	s_nop 0
	s_waitcnt lgkmcnt(1)
	v_mfma_f32_16x16x32_bf16 v[152:155], v[226:229], v[24:27], v[152:155]
	s_nop 0
	s_waitcnt lgkmcnt(0)
	v_mfma_f32_16x16x32_bf16 v[24:27], v[230:233], v[24:27], v[28:31]
	v_add_u32_e32 v156, s89, v111
	s_nop 1
	ds_read_b128 v[28:31], v156
	s_waitcnt lgkmcnt(0)
	v_mfma_f32_16x16x32_bf16 v[28:31], v[28:31], v[20:23], v[88:91]
	s_nop 2
	ds_read_b128 v[88:91], v156 offset:4096
	s_waitcnt lgkmcnt(0)
	v_mfma_f32_16x16x32_bf16 v[88:91], v[88:91], v[20:23], v[92:95]
	s_nop 2
	ds_read_b128 v[92:95], v156 offset:8192
	s_waitcnt lgkmcnt(0)
	v_mfma_f32_16x16x32_bf16 v[92:95], v[92:95], v[20:23], v[152:155]
	s_nop 2
	ds_read_b128 v[152:155], v156 offset:12288
	s_waitcnt lgkmcnt(0)
	v_mfma_f32_16x16x32_bf16 v[20:23], v[152:155], v[20:23], v[24:27]
	v_add_u32_e32 v156, s89, v113
	s_nop 1
	ds_read_b128 v[226:229], v156
	ds_read_b128 v[230:233], v156 offset:4096
	ds_read_b128 v[234:237], v156 offset:8192
	ds_read_b128 v[24:27], v156 offset:12288
	s_waitcnt lgkmcnt(3)
	v_mfma_f32_16x16x32_bf16 v[152:155], v[226:229], v[12:15], v[28:31]
	s_nop 0
	s_waitcnt lgkmcnt(2)
	v_mfma_f32_16x16x32_bf16 v[88:91], v[230:233], v[12:15], v[88:91]
	s_nop 0
	s_waitcnt lgkmcnt(1)
	v_mfma_f32_16x16x32_bf16 v[92:95], v[234:237], v[12:15], v[92:95]
	s_nop 0
	s_waitcnt lgkmcnt(0)
; __device__ __forceinline__ unsigned cvt_pk(float lo, float hi) { unsigned r; asm volatile("v_cvt_pk_bf16_f32 %0, %1, %2" : "=v"(r) : "v"(lo), "v"(hi)); return r; }
; #define Q_LOAD(j) do { const size_t r = (size_t)(rfirst + rstep * ((j) * 128 + wid * 16 + li)); \
;           _Pragma("unroll") for (int ks = 0; ks < 4; ++ks) qf[ks] = *(const bf16x8*)(Q0 + r * 512 + h * 128 + ks * 32 + kq * 8); } while (0)
; template <int SPLIT> __device__ __forceinline__ void scan_item(const Params& p, unsigned char* smem, const int item, const int vh) {
;     ...
;             mm16<NBV>(acc2, CS + vh * 16384, qf, lane);
;             __builtin_amdgcn_sched_barrier(0);
;             Q_LOAD(jn);
; #pragma unroll
;             for (int nb = 0; nb < NBV; ++nb) acc2[nb] *= exl;
;             __builtin_amdgcn_sched_barrier(0);
;             { bf16x8 pf[4]; ldfrag(pf, KP, wid, lane); mm16<NBV>(acc2, VT + vh * 16384, pf, lane); }
;             __builtin_amdgcn_sched_barrier(0);
;             { bf16_t* hp = P0 + rowl * LDP + dir * 512 + h * 128 + vh * 64 + kq * 4;
; #pragma unroll
;               for (int nb = 0; nb < NBV; ++nb) { u32x2 o; o.x = cvt_pk(acc2[nb][0] * hinv, acc2[nb][1] * hinv); o.y = cvt_pk(acc2[nb][2] * hinv, acc2[nb][3] * hinv);
;                   *(u32x2*)(hp + nb * 16) = o; } }
;             __builtin_amdgcn_sched_barrier(0);
;             float nnew;
;             { bf16x8 vf[4]; ldfrag(vf, VT, vblk, lane);
; #pragma unroll
;               for (int nb = 0; nb < NBV; ++nb) Cacc[nb] *= decay;
;               mm16<NBV>(Cacc, KT + kh * 16384, vf, lane);
	v_mfma_f32_16x16x32_bf16 v[156:159], v[24:27], v[12:15], v[20:23]
	s_nop 0
	v_add_u32_e32 v12, s0, v96
	v_mul_lo_u32 v12, v12, s3
	v_add_u32_e32 v12, s33, v12
	v_ashrrev_i32_e32 v13, 31, v12
	v_lshlrev_b64 v[12:13], 10, v[12:13]
	v_lshl_add_u64 v[12:13], v[76:77], 0, v[12:13]
	global_load_dwordx4 v[28:31], v[12:13], off
	global_load_dwordx4 v[24:27], v[12:13], off offset:64
	global_load_dwordx4 v[20:23], v[12:13], off offset:128
	s_nop 0
	global_load_dwordx4 v[12:15], v[12:13], off offset:192
	v_pk_mul_f32 v[154:155], v[86:87], v[154:155] op_sel_hi:[0,1]
	v_pk_mul_f32 v[152:153], v[86:87], v[152:153] op_sel_hi:[0,1]
	v_pk_mul_f32 v[90:91], v[86:87], v[90:91] op_sel_hi:[0,1]
	v_pk_mul_f32 v[88:89], v[86:87], v[88:89] op_sel_hi:[0,1]
	v_pk_mul_f32 v[94:95], v[86:87], v[94:95] op_sel_hi:[0,1]
	v_rcp_f32_e32 v151, v151
	v_pk_mul_f32 v[92:93], v[86:87], v[92:93] op_sel_hi:[0,1]
	v_pk_mul_f32 v[158:159], v[86:87], v[158:159] op_sel_hi:[0,1]
	v_pk_mul_f32 v[156:157], v[86:87], v[156:157] op_sel_hi:[0,1]
	v_add_u32_e32 v86, s90, v107
	ds_read_b128 v[160:163], v86 offset:32768
	v_add_u32_e32 v164, v115, v114
	ds_read_b128 v[164:167], v164
	ds_read_b128 v[172:175], v86 offset:36864
	v_add_u32_e32 v168, v116, v114
	ds_read_b128 v[178:181], v168
	s_waitcnt lgkmcnt(1)
	v_mfma_f32_16x16x32_bf16 v[88:91], v[172:175], v[164:167], v[88:91]
	v_add_u32_e32 v168, v118, v114
	ds_read_b128 v[172:175], v86 offset:45056
	v_mfma_f32_16x16x32_bf16 v[152:155], v[160:163], v[164:167], v[152:155]
	ds_read_b128 v[160:163], v86 offset:40960
	v_add_u32_e32 v86, v117, v114
	s_waitcnt lgkmcnt(0)
	v_mfma_f32_16x16x32_bf16 v[92:95], v[160:163], v[164:167], v[92:95]
	ds_read_b128 v[160:163], v86
	ds_read_b128 v[182:185], v168
	v_mfma_f32_16x16x32_bf16 v[156:159], v[172:175], v[164:167], v[156:159]
	v_add_u32_e32 v86, s90, v109
	ds_read_b128 v[226:229], v86 offset:32768
	ds_read_b128 v[230:233], v86 offset:36864
	ds_read_b128 v[234:237], v86 offset:40960
	ds_read_b128 v[164:167], v86 offset:45056
	s_waitcnt lgkmcnt(3)
	v_mfma_f32_16x16x32_bf16 v[152:155], v[226:229], v[178:181], v[152:155]
	s_nop 0
	s_waitcnt lgkmcnt(2)
	v_mfma_f32_16x16x32_bf16 v[88:91], v[230:233], v[178:181], v[88:91]
	s_nop 0
	s_waitcnt lgkmcnt(1)
	v_mfma_f32_16x16x32_bf16 v[92:95], v[234:237], v[178:181], v[92:95]
	s_nop 0
	s_waitcnt lgkmcnt(0)
	v_mfma_f32_16x16x32_bf16 v[156:159], v[164:167], v[178:181], v[156:159]
	s_nop 0
	v_add_u32_e32 v86, s90, v111
	ds_read_b128 v[226:229], v86 offset:32768
	ds_read_b128 v[230:233], v86 offset:36864
	ds_read_b128 v[234:237], v86 offset:40960
	ds_read_b128 v[164:167], v86 offset:45056
	s_waitcnt lgkmcnt(3)
	v_mfma_f32_16x16x32_bf16 v[152:155], v[226:229], v[160:163], v[152:155]
	s_nop 0
	s_waitcnt lgkmcnt(2)
	v_mfma_f32_16x16x32_bf16 v[88:91], v[230:233], v[160:163], v[88:91]
	s_nop 0
	s_waitcnt lgkmcnt(1)
	v_mfma_f32_16x16x32_bf16 v[92:95], v[234:237], v[160:163], v[92:95]
	s_nop 0
	s_waitcnt lgkmcnt(0)
	v_mfma_f32_16x16x32_bf16 v[156:159], v[164:167], v[160:163], v[156:159]
	s_nop 0
	v_add_u32_e32 v250, s90, v113
	ds_read_b128 v[218:221], v250 offset:32768
	ds_read_b128 v[222:225], v250 offset:36864
	ds_read_b128 v[226:229], v250 offset:40960
	ds_read_b128 v[230:233], v250 offset:45056
	v_add_u32_e32 v86, s90, v113
	s_nop 0
	s_waitcnt lgkmcnt(3)
	v_mfma_f32_16x16x32_bf16 v[152:155], v[218:221], v[182:185], v[152:155]
	s_nop 0
	s_waitcnt lgkmcnt(2)
	v_mfma_f32_16x16x32_bf16 v[88:91], v[222:225], v[182:185], v[88:91]
	s_nop 0
	s_waitcnt lgkmcnt(1)
	v_mfma_f32_16x16x32_bf16 v[92:95], v[226:229], v[182:185], v[92:95]
	s_nop 0
	s_waitcnt lgkmcnt(0)
	v_mfma_f32_16x16x32_bf16 v[156:159], v[230:233], v[182:185], v[156:159]
	v_mul_f32_e32 v86, v151, v152
	v_mul_f32_e32 v152, v151, v153
	v_cvt_pk_bf16_f32 v152, v86, v152
	v_mul_f32_e32 v86, v151, v154
	v_mul_f32_e32 v153, v151, v155
	v_mad_i64_i32 v[160:161], s[4:5], v131, s88, v[78:79]
	v_cvt_pk_bf16_f32 v153, v86, v153
	v_mul_f32_e32 v86, v151, v88
	v_mul_f32_e32 v88, v151, v89
	global_store_dwordx2 v[160:161], v[152:153], off
	v_cvt_pk_bf16_f32 v88, v86, v88
	v_mul_f32_e32 v86, v151, v90
	v_mul_f32_e32 v89, v151, v91
	v_cvt_pk_bf16_f32 v89, v86, v89
	global_store_dwordx2 v[160:161], v[88:89], off offset:32
	v_mul_f32_e32 v86, v151, v92
	v_mul_f32_e32 v88, v151, v93
	v_cvt_pk_bf16_f32 v88, v86, v88
	v_mul_f32_e32 v86, v151, v94
	v_mul_f32_e32 v89, v151, v95
	v_cvt_pk_bf16_f32 v89, v86, v89
	global_store_dwordx2 v[160:161], v[88:89], off offset:64
	v_mul_f32_e32 v86, v151, v156
	v_mul_f32_e32 v88, v151, v157
	v_cvt_pk_bf16_f32 v88, v86, v88
	v_mul_f32_e32 v86, v151, v158
	v_mul_f32_e32 v89, v151, v159
	v_cvt_pk_bf16_f32 v89, v86, v89
	global_store_dwordx2 v[160:161], v[88:89], off offset:96
	v_add_u32_e32 v86, v120, v107
	ds_read_b128 v[88:91], v86
	v_add_u32_e32 v92, v115, v119
	ds_read_b128 v[92:95], v92 offset:32768
	ds_read_b128 v[152:155], v86 offset:4096
	v_add_u32_e32 v151, v116, v119
	v_pk_mul_f32 v[50:51], v[50:51], v[84:85] op_sel_hi:[1,0]
	v_pk_mul_f32 v[48:49], v[48:49], v[84:85] op_sel_hi:[1,0]
	ds_read_b128 v[156:159], v151 offset:32768
	ds_read_b128 v[160:163], v86 offset:8192
	v_add_u32_e32 v151, v117, v119
	v_pk_mul_f32 v[54:55], v[54:55], v[84:85] op_sel_hi:[1,0]
	s_waitcnt lgkmcnt(3)
	v_mfma_f32_16x16x32_bf16 v[48:51], v[88:91], v[92:95], v[48:51]
	ds_read_b128 v[88:91], v86 offset:12288
	v_pk_mul_f32 v[52:53], v[52:53], v[84:85] op_sel_hi:[1,0]
	v_pk_mul_f32 v[58:59], v[58:59], v[84:85] op_sel_hi:[1,0]
	v_pk_mul_f32 v[56:57], v[56:57], v[84:85] op_sel_hi:[1,0]
	s_waitcnt lgkmcnt(3)
; __device__ __forceinline__ unsigned cvt_pk(float lo, float hi) { unsigned r; asm volatile("v_cvt_pk_bf16_f32 %0, %1, %2" : "=v"(r) : "v"(lo), "v"(hi)); return r; }
; __device__ __forceinline__ float bflo(unsigned w) { return __uint_as_float(w << 16); }
; __device__ __forceinline__ float bfhi(unsigned w) { return __uint_as_float(w & 0xffff0000u); }
; template <int SPLIT> __device__ __forceinline__ void scan_item(const Params& p, unsigned char* smem, const int item, const int vh) {
;     ...
;             { bf16x8 vf[4]; ldfrag(vf, VT, vblk, lane);
; #pragma unroll
;               for (int nb = 0; nb < NBV; ++nb) Cacc[nb] *= decay;
;               mm16<NBV>(Cacc, KT + kh * 16384, vf, lane);
;               float part = 0.f;
; #pragma unroll
;               for (int ks = 0; ks < 4; ++ks) { const u32x4 kw = *(const u32x4*)(KT + swz(wid * 16 + li, ks * 4 + kq));
;                   part += bflo(kw.x) + bfhi(kw.x) + bflo(kw.y) + bfhi(kw.y) + bflo(kw.z) + bfhi(kw.z) + bflo(kw.w) + bfhi(kw.w); }
;               part += __shfl_xor(part, 16); part += __shfl_xor(part, 32);
;               nnew = decay * n_s[wid * 16 + li] + part; }
;             __syncthreads();
; #pragma unroll
;             for (int nb = 0; nb < NBV; ++nb) { u32x2 o; o.x = cvt_pk(Cacc[nb][0], Cacc[nb][1]); o.y = cvt_pk(Cacc[nb][2], Cacc[nb][3]);
;                 *(u32x2*)(CS + swz(vblk * 16 + li, (kh * 4 + nb) * 2 + (kq >> 1)) + (kq & 1) * 8) = o; }
;             if (kq == 0) n_s[wid * 16 + li] = nnew;
	v_mfma_f32_16x16x32_bf16 v[52:55], v[152:155], v[92:95], v[52:55]
	v_add_u32_e32 v86, v118, v119
	v_pk_mul_f32 v[62:63], v[62:63], v[84:85] op_sel_hi:[1,0]
	v_pk_mul_f32 v[60:61], v[60:61], v[84:85] op_sel_hi:[1,0]
	s_waitcnt lgkmcnt(1)
	v_mfma_f32_16x16x32_bf16 v[56:59], v[160:163], v[92:95], v[56:59]
	ds_read_b128 v[152:155], v151 offset:32768
	ds_read_b128 v[160:163], v86 offset:32768
	s_waitcnt lgkmcnt(2)
	v_mfma_f32_16x16x32_bf16 v[60:63], v[88:91], v[92:95], v[60:63]
	v_add_u32_e32 v251, v120, v109
	ds_read_b128 v[218:221], v251
	ds_read_b128 v[222:225], v251 offset:4096
	ds_read_b128 v[226:229], v251 offset:8192
	ds_read_b128 v[230:233], v251 offset:12288
	v_add_u32_e32 v252, v120, v111
	ds_read_b128 v[234:237], v252
	v_add_u32_e32 v86, v120, v109
	ds_read_b128 v[238:241], v252 offset:4096
	s_waitcnt lgkmcnt(5)
	v_mfma_f32_16x16x32_bf16 v[48:51], v[218:221], v[156:159], v[48:51]
	ds_read_b128 v[218:221], v252 offset:8192
	s_waitcnt lgkmcnt(5)
	v_mfma_f32_16x16x32_bf16 v[52:55], v[222:225], v[156:159], v[52:55]
	ds_read_b128 v[222:225], v252 offset:12288
	s_waitcnt lgkmcnt(5)
	v_mfma_f32_16x16x32_bf16 v[56:59], v[226:229], v[156:159], v[56:59]
	v_add_u32_e32 v253, v120, v113
	ds_read_b128 v[226:229], v253
	s_waitcnt lgkmcnt(5)
	v_mfma_f32_16x16x32_bf16 v[60:63], v[230:233], v[156:159], v[60:63]
	v_add_u32_e32 v86, v120, v111
	ds_read_b128 v[230:233], v253 offset:4096
	s_waitcnt lgkmcnt(5)
	v_mfma_f32_16x16x32_bf16 v[48:51], v[234:237], v[152:155], v[48:51]
	ds_read_b128 v[234:237], v253 offset:8192
	s_waitcnt lgkmcnt(5)
	v_mfma_f32_16x16x32_bf16 v[52:55], v[238:241], v[152:155], v[52:55]
	ds_read_b128 v[238:241], v253 offset:12288
	s_waitcnt lgkmcnt(5)
	v_mfma_f32_16x16x32_bf16 v[56:59], v[218:221], v[152:155], v[56:59]
	s_nop 0
	s_waitcnt lgkmcnt(4)
	v_mfma_f32_16x16x32_bf16 v[60:63], v[222:225], v[152:155], v[60:63]
	v_add_u32_e32 v86, v120, v113
	s_nop 0
	s_waitcnt lgkmcnt(3)
	v_mfma_f32_16x16x32_bf16 v[48:51], v[226:229], v[160:163], v[48:51]
	s_nop 0
	s_waitcnt lgkmcnt(2)
	v_mfma_f32_16x16x32_bf16 v[52:55], v[230:233], v[160:163], v[52:55]
	s_nop 0
	s_waitcnt lgkmcnt(1)
	v_mfma_f32_16x16x32_bf16 v[56:59], v[234:237], v[160:163], v[56:59]
	s_nop 0
	s_waitcnt lgkmcnt(0)
	v_mfma_f32_16x16x32_bf16 v[60:63], v[238:241], v[160:163], v[60:63]
	v_add_u32_e32 v86, v121, v106
	ds_read_b128 v[88:91], v86
	s_waitcnt lgkmcnt(0)
	v_lshlrev_b32_e32 v86, 16, v88
	v_and_b32_e32 v88, 0xffff0000, v88
	v_add_f32_e32 v86, v86, v88
	v_lshlrev_b32_e32 v88, 16, v89
	v_add_f32_e32 v86, v86, v88
	v_and_b32_e32 v88, 0xffff0000, v89
	v_add_f32_e32 v86, v86, v88
	v_lshlrev_b32_e32 v88, 16, v90
	v_add_f32_e32 v86, v86, v88
	v_and_b32_e32 v88, 0xffff0000, v90
	v_add_f32_e32 v86, v86, v88
	v_lshlrev_b32_e32 v88, 16, v91
	v_add_f32_e32 v86, v86, v88
	v_and_b32_e32 v88, 0xffff0000, v91
	v_add_f32_e32 v86, v86, v88
	v_add_u32_e32 v88, v121, v108
	ds_read_b128 v[88:91], v88
	v_add_f32_e32 v86, 0, v86
	s_waitcnt lgkmcnt(0)
	v_lshlrev_b32_e32 v92, 16, v88
	v_and_b32_e32 v88, 0xffff0000, v88
	v_add_f32_e32 v88, v92, v88
	v_lshlrev_b32_e32 v92, 16, v89
	v_add_f32_e32 v88, v88, v92
	v_and_b32_e32 v89, 0xffff0000, v89
	v_add_f32_e32 v88, v88, v89
	v_lshlrev_b32_e32 v89, 16, v90
	v_add_f32_e32 v88, v88, v89
	v_and_b32_e32 v89, 0xffff0000, v90
	v_add_f32_e32 v88, v88, v89
	v_lshlrev_b32_e32 v89, 16, v91
	v_add_f32_e32 v88, v88, v89
	v_and_b32_e32 v89, 0xffff0000, v91
	v_add_f32_e32 v88, v88, v89
	v_add_f32_e32 v86, v86, v88
	v_add_u32_e32 v88, v121, v110
	ds_read_b128 v[88:91], v88
	s_waitcnt lgkmcnt(0)
	v_lshlrev_b32_e32 v92, 16, v88
	v_and_b32_e32 v88, 0xffff0000, v88
	v_add_f32_e32 v88, v92, v88
	v_lshlrev_b32_e32 v92, 16, v89
	v_add_f32_e32 v88, v88, v92
	v_and_b32_e32 v89, 0xffff0000, v89
	v_add_f32_e32 v88, v88, v89
	v_lshlrev_b32_e32 v89, 16, v90
	v_add_f32_e32 v88, v88, v89
	v_and_b32_e32 v89, 0xffff0000, v90
	v_add_f32_e32 v88, v88, v89
	v_lshlrev_b32_e32 v89, 16, v91
	v_add_f32_e32 v88, v88, v89
	v_and_b32_e32 v89, 0xffff0000, v91
	v_add_f32_e32 v88, v88, v89
	v_add_f32_e32 v86, v86, v88
	v_add_u32_e32 v88, v121, v112
	ds_read_b128 v[88:91], v88
	s_waitcnt lgkmcnt(0)
	v_lshlrev_b32_e32 v92, 16, v88
	v_and_b32_e32 v88, 0xffff0000, v88
	v_add_f32_e32 v88, v92, v88
	v_lshlrev_b32_e32 v92, 16, v89
	v_add_f32_e32 v88, v88, v92
	v_and_b32_e32 v89, 0xffff0000, v89
	v_add_f32_e32 v88, v88, v89
	v_lshlrev_b32_e32 v89, 16, v90
	v_add_f32_e32 v88, v88, v89
	v_and_b32_e32 v89, 0xffff0000, v90
	v_add_f32_e32 v88, v88, v89
	v_lshlrev_b32_e32 v89, 16, v91
	v_add_f32_e32 v88, v88, v89
	v_and_b32_e32 v89, 0xffff0000, v91
	v_add_f32_e32 v88, v88, v89
	v_add_f32_e32 v86, v86, v88
	ds_bpermute_b32 v87, v87, v86
	s_waitcnt lgkmcnt(0)
	v_add_f32_e32 v86, v86, v87
	ds_bpermute_b32 v67, v67, v86
	ds_read_b32 v87, v122
	s_waitcnt lgkmcnt(0)
	s_barrier
	v_cvt_pk_bf16_f32 v88, v48, v49
	v_cvt_pk_bf16_f32 v89, v50, v51
	ds_write_b64 v146, v[88:89]
	v_cvt_pk_bf16_f32 v88, v52, v53
	v_cvt_pk_bf16_f32 v89, v54, v55
	ds_write_b64 v147, v[88:89]
	v_cvt_pk_bf16_f32 v88, v56, v57
	v_cvt_pk_bf16_f32 v89, v58, v59
	ds_write_b64 v148, v[88:89]
	v_cvt_pk_bf16_f32 v88, v60, v61
	v_cvt_pk_bf16_f32 v89, v62, v63
	ds_write_b64 v149, v[88:89]
	s_and_saveexec_b64 s[86:87], s[8:9]
	s_cbranch_execz .LBB0_311
	v_add_f32_e32 v67, v86, v67
	v_fmac_f32_e32 v67, v84, v87
	ds_write_b32 v122, v67
	s_branch .LBB0_311
